# adds SGU MFMA-section read pipelining, P3 mid-hook R loads in one batch, attention PV fragment reads issued one step ahead
# speedup vs baseline: 1.0081x; 1.0026x over previous
.LBB0_453:
	s_or_b64 exec, exec, s[0:1]
	s_lshl_b32 s0, s6, 2
	v_readlane_b32 s1, v252, 25
	s_add_i32 s34, s0, s1
	s_lshl_b32 s0, s34, 2
	s_waitcnt vmcnt(0)
	ds_write_b128 v168, v[12:15]
	ds_write_b128 v169, v[16:19]
	ds_write_b128 v170, v[20:23]
	ds_write_b128 v171, v[24:27]
	ds_write_b16 v172, v28 offset:36864
	ds_write_b16_d16_hi v172, v28 offset:37392
	ds_write_b16 v172, v29 offset:37920
	ds_write_b16_d16_hi v172, v29 offset:38448
	ds_write_b16 v172, v30 offset:38976
	ds_write_b16_d16_hi v172, v30 offset:39504
	ds_write_b16 v172, v31 offset:40032
	ds_write_b16_d16_hi v172, v31 offset:40560
	ds_write_b16 v173, v32 offset:36864
	ds_write_b16_d16_hi v173, v32 offset:37392
	ds_write_b16 v173, v33 offset:37920
	ds_write_b16_d16_hi v173, v33 offset:38448
	ds_write_b16 v173, v34 offset:38976
	ds_write_b16_d16_hi v173, v34 offset:39504
	ds_write_b16 v173, v35 offset:40032
	ds_write_b16_d16_hi v173, v35 offset:40560
	ds_write_b16 v174, v36 offset:36864
	ds_write_b16_d16_hi v174, v36 offset:37392
	ds_write_b16 v174, v37 offset:37920
	ds_write_b16_d16_hi v174, v37 offset:38448
	ds_write_b16 v174, v38 offset:38976
	ds_write_b16_d16_hi v174, v38 offset:39504
	ds_write_b16 v174, v39 offset:40032
	ds_write_b16_d16_hi v174, v39 offset:40560
	ds_write_b16 v175, v4 offset:36864
	ds_write_b16_d16_hi v175, v4 offset:37392
	ds_write_b16 v175, v5 offset:37920
	ds_write_b16_d16_hi v175, v5 offset:38448
	ds_write_b16 v175, v6 offset:38976
	ds_write_b16_d16_hi v175, v6 offset:39504
	ds_write_b16 v175, v7 offset:40032
	ds_write_b16_d16_hi v175, v7 offset:40560
	v_mov_b32_e32 v4, s0
	v_readlane_b32 s0, v254, 25
	s_waitcnt lgkmcnt(0)
	s_barrier
	v_readlane_b32 s1, v254, 26
	v_and_b32_e32 v5, 64, v237
	v_add_u32_e32 v5, 64, v5
	v_readlane_b32 s48, v254, 41
	v_readlane_b32 s49, v254, 42
	v_readlane_b32 s56, v254, 43
	global_load_dword v188, v4, s[0:1]
	v_xor_b32_e32 v4, 32, v237
	v_cmp_lt_i32_e32 vcc, v4, v5
	s_and_b64 s[86:87], s[16:17], s[48:49]
	v_readlane_b32 s57, v254, 44
	v_cndmask_b32_e32 v4, v237, v4, vcc
	v_lshlrev_b32_e32 v189, 2, v4
	ds_read_b128 v[4:7], v176
	ds_read_b128 v[8:11], v176 offset:32
	s_waitcnt lgkmcnt(1)
	v_mfma_f32_32x32x16_bf16 v[64:79], v[4:7], v[0:3], 0
	ds_read_b128 v[4:7], v176 offset:64
	v_readlane_b32 s38, v254, 45
	s_and_b64 s[88:89], s[16:17], s[56:57]
	v_readlane_b32 s39, v254, 46
	v_readlane_b32 s2, v254, 47
	s_and_b64 s[90:91], s[16:17], s[38:39]
	v_readlane_b32 s3, v254, 48
	s_waitcnt lgkmcnt(1)
	v_mfma_f32_32x32x16_bf16 v[64:79], v[8:11], v[128:131], v[64:79]
	v_readlane_b32 s40, v254, 49
	v_readlane_b32 s52, v254, 37
	s_and_b64 s[92:93], s[16:17], s[2:3]
	v_readlane_b32 s41, v254, 50
	v_readlane_b32 s42, v254, 51
	v_readlane_b32 s53, v254, 38
	v_readlane_b32 s0, v254, 39
	s_waitcnt lgkmcnt(0)
	v_mfma_f32_32x32x16_bf16 v[64:79], v[4:7], v[124:127], v[64:79]
	ds_read_b128 v[4:7], v176 offset:96
	s_and_b64 s[94:95], s[16:17], s[40:41]
	v_readlane_b32 s43, v254, 52
	v_readlane_b32 s44, v254, 53
	s_and_b64 s[82:83], s[16:17], s[52:53]
	v_readlane_b32 s1, v254, 40
	s_and_b64 s[96:97], s[16:17], s[42:43]
	s_waitcnt lgkmcnt(0)
	v_mfma_f32_32x32x16_bf16 v[64:79], v[4:7], v[120:123], v[64:79]
	ds_read_b128 v[4:7], v177
	ds_read_b128 v[8:11], v177 offset:32
	v_readlane_b32 s45, v254, 54
	v_readlane_b32 s68, v254, 55
	s_and_b64 s[84:85], s[16:17], s[0:1]
	s_and_b64 s[28:29], s[16:17], s[44:45]
	v_readlane_b32 s69, v254, 56
	v_readlane_b32 s70, v254, 57
	s_waitcnt lgkmcnt(1)
	v_mfma_f32_32x32x16_bf16 v[48:63], v[4:7], v[0:3], 0
	ds_read_b128 v[4:7], v177 offset:64
	s_nop 0
	v_mul_f32_e32 v66, 0x3e38aa3b, v66
	v_mul_f32_e32 v64, 0x3e38aa3b, v64
	v_cndmask_b32_e64 v80, v239, v64, s[82:83]
	v_mul_f32_e32 v64, 0x3e38aa3b, v65
	v_cndmask_b32_e64 v65, v239, v64, s[84:85]
	s_and_b64 s[4:5], s[16:17], s[68:69]
	s_waitcnt lgkmcnt(1)
	v_mfma_f32_32x32x16_bf16 v[48:63], v[8:11], v[128:131], v[48:63]
	v_readlane_b32 s71, v254, 58
	v_readlane_b32 s72, v254, 59
	s_and_b64 s[6:7], s[16:17], s[70:71]
	v_readlane_b32 s73, v254, 60
	v_readlane_b32 s74, v254, 61
	s_and_b64 s[8:9], s[16:17], s[72:73]
	v_readlane_b32 s75, v254, 62
	s_waitcnt lgkmcnt(0)
	v_mfma_f32_32x32x16_bf16 v[48:63], v[4:7], v[124:127], v[48:63]
	ds_read_b128 v[4:7], v177 offset:96
	v_readlane_b32 s76, v254, 63
	s_and_b64 s[10:11], s[16:17], s[74:75]
	v_readlane_b32 s77, v255, 0
	v_readlane_b32 s78, v255, 1
	s_and_b64 s[12:13], s[16:17], s[76:77]
	v_readlane_b32 s79, v255, 2
	s_waitcnt lgkmcnt(0)
	v_mfma_f32_32x32x16_bf16 v[48:63], v[4:7], v[120:123], v[48:63]
	ds_read_b128 v[4:7], v178
	ds_read_b128 v[8:11], v178 offset:32
	v_readlane_b32 s36, v255, 3
	s_and_b64 s[14:15], s[16:17], s[78:79]
	v_readlane_b32 s37, v255, 4
	s_and_b64 s[18:19], s[16:17], s[36:37]
	v_readlane_b32 s80, v252, 57
	v_readlane_b32 s81, v252, 58
	s_waitcnt lgkmcnt(1)
	v_mfma_f32_32x32x16_bf16 v[32:47], v[4:7], v[0:3], 0
	ds_read_b128 v[4:7], v178 offset:64
	s_nop 0
	v_mul_f32_e32 v48, 0x3e38aa3b, v48
	s_waitcnt vmcnt(0)
	v_mul_f32_e32 v190, 0x3fb8aa3b, v188
	v_max3_f32 v64, v190, v80, v65
	v_readlane_b32 s0, v255, 5
	v_readlane_b32 s1, v255, 6
	s_add_i32 s31, s31, 1
	s_waitcnt lgkmcnt(1)
	v_mfma_f32_32x32x16_bf16 v[32:47], v[8:11], v[128:131], v[32:47]
	s_add_i32 s51, s51, 32
	s_waitcnt lgkmcnt(0)
	v_mfma_f32_32x32x16_bf16 v[32:47], v[4:7], v[124:127], v[32:47]
	ds_read_b128 v[4:7], v178 offset:96
	s_waitcnt lgkmcnt(0)
	v_mfma_f32_32x32x16_bf16 v[32:47], v[4:7], v[120:123], v[32:47]
	ds_read_b128 v[4:7], v179
	ds_read_b128 v[8:11], v179 offset:32
	s_waitcnt lgkmcnt(1)
	v_mfma_f32_32x32x16_bf16 v[16:31], v[4:7], v[0:3], 0
	ds_read_b128 v[4:7], v179 offset:64
	s_nop 6
	v_mul_f32_e32 v32, 0x3e38aa3b, v32
	s_waitcnt lgkmcnt(1)
	v_mfma_f32_32x32x16_bf16 v[16:31], v[8:11], v[128:131], v[16:31]
	s_waitcnt lgkmcnt(0)
	v_mfma_f32_32x32x16_bf16 v[16:31], v[4:7], v[124:127], v[16:31]
	ds_read_b128 v[4:7], v179 offset:96
	s_waitcnt lgkmcnt(0)
	v_mfma_f32_32x32x16_bf16 v[16:31], v[4:7], v[120:123], v[16:31]
	ds_read_b128 v[4:7], v180
	ds_read_b128 v[192:195], v180 offset:32
	s_waitcnt lgkmcnt(1)
	v_mfma_f32_32x32x16_bf16 v[0:15], v[4:7], v[0:3], 0
	s_nop 7
	v_mul_f32_e32 v16, 0x3e38aa3b, v16
	s_waitcnt lgkmcnt(0)
	v_mfma_f32_32x32x16_bf16 v[0:15], v[192:195], v[128:131], v[0:15]
	ds_read_b128 v[128:131], v180 offset:64
	s_waitcnt lgkmcnt(0)
	v_mfma_f32_32x32x16_bf16 v[0:15], v[128:131], v[124:127], v[0:15]
	ds_read_b128 v[124:127], v180 offset:96
	v_cndmask_b32_e64 v131, v239, v48, s[16:17]
	v_mul_f32_e32 v48, 0x3e38aa3b, v49
	v_mul_f32_e32 v49, 0x3e38aa3b, v50
	v_cndmask_b32_e64 v50, v239, v49, s[16:17]
	v_mul_f32_e32 v49, 0x3e38aa3b, v51
	v_cndmask_b32_e64 v51, v239, v49, s[16:17]
	s_waitcnt lgkmcnt(0)
	v_mfma_f32_32x32x16_bf16 v[0:15], v[124:127], v[120:123], v[0:15]
	v_cndmask_b32_e64 v120, v239, v66, s[86:87]
	v_mul_f32_e32 v66, 0x3e38aa3b, v67
	v_cndmask_b32_e64 v67, v239, v66, s[88:89]
	v_mul_f32_e32 v66, 0x3e38aa3b, v68
	v_cndmask_b32_e64 v121, v239, v66, s[90:91]
	v_mul_f32_e32 v66, 0x3e38aa3b, v69
	v_mul_f32_e32 v49, 0x3e38aa3b, v52
	v_cndmask_b32_e64 v69, v239, v66, s[92:93]
	v_mul_f32_e32 v66, 0x3e38aa3b, v70
	v_cndmask_b32_e64 v52, v239, v49, s[16:17]
	v_mul_f32_e32 v49, 0x3e38aa3b, v53
	v_cndmask_b32_e64 v70, v239, v66, s[94:95]
	v_mul_f32_e32 v66, 0x3e38aa3b, v71
	v_cndmask_b32_e64 v53, v239, v49, s[16:17]
	v_mul_f32_e32 v49, 0x3e38aa3b, v54
	v_cndmask_b32_e64 v71, v239, v66, s[96:97]
	v_mul_f32_e32 v66, 0x3e38aa3b, v72
	v_cndmask_b32_e64 v54, v239, v49, s[16:17]
	v_mul_f32_e32 v49, 0x3e38aa3b, v55
	v_cndmask_b32_e64 v72, v239, v66, s[28:29]
	v_mul_f32_e32 v66, 0x3e38aa3b, v73
	v_cndmask_b32_e64 v192, v239, v49, s[16:17]
	v_mul_f32_e32 v49, 0x3e38aa3b, v56
	v_cndmask_b32_e64 v126, v239, v66, s[4:5]
	v_mul_f32_e32 v66, 0x3e38aa3b, v74
	v_cndmask_b32_e64 v193, v239, v49, s[16:17]
	v_mul_f32_e32 v49, 0x3e38aa3b, v57
	v_max3_f32 v64, v64, v120, v67
	v_cndmask_b32_e64 v127, v239, v66, s[6:7]
	v_mul_f32_e32 v66, 0x3e38aa3b, v75
	v_cndmask_b32_e64 v194, v239, v49, s[16:17]
	v_mul_f32_e32 v49, 0x3e38aa3b, v58
	v_max3_f32 v64, v64, v121, v69
	v_cndmask_b32_e64 v75, v239, v66, s[8:9]
	v_mul_f32_e32 v66, 0x3e38aa3b, v76
	v_cndmask_b32_e64 v58, v239, v49, s[16:17]
	v_mul_f32_e32 v49, 0x3e38aa3b, v59
	v_max3_f32 v64, v64, v70, v71
	v_cndmask_b32_e64 v128, v239, v66, s[10:11]
	v_mul_f32_e32 v66, 0x3e38aa3b, v77
	v_cndmask_b32_e64 v195, v239, v49, s[16:17]
	v_mul_f32_e32 v49, 0x3e38aa3b, v60
	v_max3_f32 v64, v64, v72, v126
	v_cndmask_b32_e64 v77, v239, v66, s[12:13]
	v_mul_f32_e32 v66, 0x3e38aa3b, v78
	v_cndmask_b32_e64 v196, v239, v49, s[16:17]
	v_mul_f32_e32 v49, 0x3e38aa3b, v61
	v_max3_f32 v64, v64, v127, v75
	v_cndmask_b32_e64 v129, v239, v66, s[14:15]
	v_mul_f32_e32 v66, 0x3e38aa3b, v79
	v_cndmask_b32_e64 v197, v239, v49, s[16:17]
	v_mul_f32_e32 v49, 0x3e38aa3b, v62
	v_max3_f32 v64, v64, v128, v77
	v_cndmask_b32_e64 v130, v239, v66, s[18:19]
	v_cndmask_b32_e64 v198, v239, v49, s[16:17]
	v_mul_f32_e32 v49, 0x3e38aa3b, v63
	v_max3_f32 v64, v64, v129, v130
	v_cndmask_b32_e64 v191, v239, v48, s[16:17]
	v_cndmask_b32_e64 v199, v239, v49, s[16:17]
	s_or_b64 s[16:17], s[16:17], s[80:81]
	v_max3_f32 v48, v64, v131, v191
	v_cndmask_b32_e64 v200, v239, v32, s[16:17]
	v_mul_f32_e32 v32, 0x3e38aa3b, v33
	v_mul_f32_e32 v33, 0x3e38aa3b, v34
	v_max3_f32 v48, v48, v50, v51
	v_cndmask_b32_e64 v202, v239, v33, s[16:17]
	v_mul_f32_e32 v33, 0x3e38aa3b, v35
	v_max3_f32 v48, v48, v52, v53
	v_cndmask_b32_e64 v203, v239, v33, s[16:17]
	v_mul_f32_e32 v33, 0x3e38aa3b, v36
	v_max3_f32 v48, v48, v54, v192
	v_cndmask_b32_e64 v204, v239, v33, s[16:17]
	v_mul_f32_e32 v33, 0x3e38aa3b, v37
	v_max3_f32 v48, v48, v193, v194
	v_cndmask_b32_e64 v205, v239, v33, s[16:17]
	v_mul_f32_e32 v33, 0x3e38aa3b, v38
	v_max3_f32 v48, v48, v58, v195
	v_cndmask_b32_e64 v206, v239, v33, s[16:17]
	v_mul_f32_e32 v33, 0x3e38aa3b, v39
	v_cndmask_b32_e64 v74, v239, v16, s[16:17]
	v_mul_f32_e32 v16, 0x3e38aa3b, v17
	v_mul_f32_e32 v17, 0x3e38aa3b, v18
	v_max3_f32 v48, v48, v196, v197
	v_cndmask_b32_e64 v207, v239, v33, s[16:17]
	v_mul_f32_e32 v33, 0x3e38aa3b, v40
	v_cndmask_b32_e64 v68, v239, v17, s[16:17]
	v_mul_f32_e32 v17, 0x3e38aa3b, v19
	v_max3_f32 v48, v48, v198, v199
	v_cndmask_b32_e64 v201, v239, v32, s[16:17]
	v_cndmask_b32_e64 v208, v239, v33, s[16:17]
	v_mul_f32_e32 v33, 0x3e38aa3b, v41
	v_cndmask_b32_e64 v66, v239, v17, s[16:17]
	v_mul_f32_e32 v17, 0x3e38aa3b, v20
	v_max3_f32 v32, v48, v200, v201
	v_cndmask_b32_e64 v125, v239, v33, s[16:17]
	v_mul_f32_e32 v33, 0x3e38aa3b, v42
	v_cndmask_b32_e64 v64, v239, v17, s[16:17]
	v_mul_f32_e32 v17, 0x3e38aa3b, v21
	v_max3_f32 v32, v32, v202, v203
	v_cndmask_b32_e64 v124, v239, v33, s[16:17]
	v_mul_f32_e32 v33, 0x3e38aa3b, v43
	v_cndmask_b32_e64 v62, v239, v17, s[16:17]
	v_mul_f32_e32 v17, 0x3e38aa3b, v22
	v_max3_f32 v32, v32, v204, v205
	v_cndmask_b32_e64 v123, v239, v33, s[16:17]
	v_mul_f32_e32 v33, 0x3e38aa3b, v44
	v_cndmask_b32_e64 v60, v239, v17, s[16:17]
	v_mul_f32_e32 v17, 0x3e38aa3b, v23
	v_max3_f32 v32, v32, v206, v207
	v_cndmask_b32_e64 v122, v239, v33, s[16:17]
	v_mul_f32_e32 v33, 0x3e38aa3b, v45
	v_cndmask_b32_e64 v57, v239, v17, s[16:17]
	v_mul_f32_e32 v17, 0x3e38aa3b, v24
	v_max3_f32 v32, v32, v208, v125
	v_cndmask_b32_e64 v79, v239, v33, s[16:17]
	v_mul_f32_e32 v33, 0x3e38aa3b, v46
	v_cndmask_b32_e64 v59, v239, v17, s[16:17]
	v_mul_f32_e32 v17, 0x3e38aa3b, v25
	v_max3_f32 v32, v32, v124, v123
	v_cndmask_b32_e64 v78, v239, v33, s[16:17]
	v_mul_f32_e32 v33, 0x3e38aa3b, v47
	v_cndmask_b32_e64 v48, v239, v17, s[16:17]
	v_mul_f32_e32 v17, 0x3e38aa3b, v26
	v_max3_f32 v32, v32, v122, v79
	v_cndmask_b32_e64 v76, v239, v33, s[16:17]
	v_cndmask_b32_e64 v55, v239, v17, s[16:17]
	v_mul_f32_e32 v17, 0x3e38aa3b, v27
	v_max3_f32 v32, v32, v78, v76
	v_cndmask_b32_e64 v73, v239, v16, s[16:17]
	v_cndmask_b32_e64 v45, v239, v17, s[16:17]
	v_mul_f32_e32 v17, 0x3e38aa3b, v28
	v_mul_f32_e32 v0, 0x3e38aa3b, v0
	v_max3_f32 v16, v32, v74, v73
	v_cndmask_b32_e64 v46, v239, v17, s[16:17]
	v_mul_f32_e32 v17, 0x3e38aa3b, v29
	v_cndmask_b32_e64 v24, v0, v239, s[52:53]
	v_mul_f32_e32 v0, 0x3e38aa3b, v1
	v_mul_f32_e32 v1, 0x3e38aa3b, v2
	v_max3_f32 v16, v16, v68, v66
	v_cndmask_b32_e64 v27, v239, v17, s[16:17]
	v_mul_f32_e32 v17, 0x3e38aa3b, v30
	v_cndmask_b32_e64 v30, v1, v239, s[48:49]
	v_mul_f32_e32 v1, 0x3e38aa3b, v3
	v_max3_f32 v16, v16, v64, v62
	v_cndmask_b32_e64 v25, v1, v239, s[56:57]
	v_mul_f32_e32 v1, 0x3e38aa3b, v4
	v_max3_f32 v16, v16, v60, v57
	v_cndmask_b32_e64 v26, v1, v239, s[38:39]
	v_mul_f32_e32 v1, 0x3e38aa3b, v5
	v_max3_f32 v16, v16, v59, v48
	v_cndmask_b32_e64 v21, v1, v239, s[2:3]
	v_mul_f32_e32 v1, 0x3e38aa3b, v6
	v_max3_f32 v16, v16, v55, v45
	v_cndmask_b32_e64 v28, v239, v17, s[16:17]
	v_mul_f32_e32 v17, 0x3e38aa3b, v31
	v_cndmask_b32_e64 v22, v1, v239, s[40:41]
	v_mul_f32_e32 v1, 0x3e38aa3b, v7
	v_max3_f32 v16, v16, v46, v27
	v_cndmask_b32_e64 v23, v239, v17, s[16:17]
	v_cndmask_b32_e64 v19, v1, v239, s[42:43]
	v_mul_f32_e32 v1, 0x3e38aa3b, v8
	v_max3_f32 v16, v16, v28, v23
	v_cndmask_b32_e64 v29, v239, v0, s[0:1]
	v_cndmask_b32_e64 v20, v1, v239, s[44:45]
	v_mul_f32_e32 v1, 0x3e38aa3b, v9
	v_max3_f32 v0, v16, v24, v29
	v_cndmask_b32_e64 v17, v1, v239, s[68:69]
	v_mul_f32_e32 v1, 0x3e38aa3b, v10
	v_max3_f32 v0, v0, v30, v25
	v_cndmask_b32_e64 v18, v1, v239, s[70:71]
	v_mul_f32_e32 v1, 0x3e38aa3b, v11
	v_max3_f32 v0, v0, v26, v21
	v_cndmask_b32_e64 v16, v1, v239, s[72:73]
	v_mul_f32_e32 v1, 0x3e38aa3b, v12
	v_max3_f32 v0, v0, v22, v19
	v_cndmask_b32_e64 v12, v1, v239, s[74:75]
	v_mul_f32_e32 v1, 0x3e38aa3b, v13
	v_max3_f32 v0, v0, v20, v17
	v_cndmask_b32_e64 v10, v1, v239, s[76:77]
	v_mul_f32_e32 v1, 0x3e38aa3b, v14
	v_max3_f32 v0, v0, v18, v16
	v_cndmask_b32_e64 v11, v1, v239, s[78:79]
	v_mul_f32_e32 v1, 0x3e38aa3b, v15
	v_max3_f32 v0, v0, v12, v10
	v_cndmask_b32_e64 v9, v1, v239, s[36:37]
	v_max3_f32 v0, v0, v11, v9
	ds_bpermute_b32 v1, v189, v0
	s_mov_b32 s80, 0x3fb8aa3b
	s_waitcnt lgkmcnt(0)
	v_max_f32_e32 v1, v1, v1
	v_max_f32_e32 v8, v0, v1
	v_sub_f32_e32 v0, v80, v8
	v_exp_f32_e32 v0, v0
	v_sub_f32_e32 v1, v65, v8
	v_exp_f32_e32 v1, v1
	v_sub_f32_e32 v14, v72, v8
	v_add_f32_e32 v2, 0, v0
	v_exp_f32_e32 v32, v14
	v_add_f32_e32 v3, v2, v1
	v_sub_f32_e32 v2, v120, v8
	v_exp_f32_e32 v2, v2
	v_sub_f32_e32 v14, v126, v8
	v_exp_f32_e32 v33, v14
	v_sub_f32_e32 v14, v127, v8
	v_add_f32_e32 v4, v3, v2
	v_sub_f32_e32 v3, v67, v8
	v_exp_f32_e32 v3, v3
	v_exp_f32_e32 v34, v14
	v_sub_f32_e32 v14, v75, v8
	v_exp_f32_e32 v36, v14
	v_add_f32_e32 v5, v4, v3
	v_sub_f32_e32 v4, v121, v8
	v_exp_f32_e32 v4, v4
	v_sub_f32_e32 v14, v128, v8
	v_exp_f32_e32 v38, v14
	v_sub_f32_e32 v14, v77, v8
	v_add_f32_e32 v6, v5, v4
	v_sub_f32_e32 v5, v69, v8
	v_exp_f32_e32 v5, v5
	v_exp_f32_e32 v39, v14
	v_sub_f32_e32 v14, v129, v8
	v_exp_f32_e32 v44, v14
	v_add_f32_e32 v7, v6, v5
	v_sub_f32_e32 v6, v70, v8
	v_exp_f32_e32 v6, v6
	v_sub_f32_e32 v14, v130, v8
	v_exp_f32_e32 v49, v14
	v_sub_f32_e32 v14, v131, v8
	v_add_f32_e32 v13, v7, v6
	v_sub_f32_e32 v7, v71, v8
	v_exp_f32_e32 v7, v7
	v_exp_f32_e32 v35, v14
	v_sub_f32_e32 v14, v191, v8
	v_exp_f32_e32 v37, v14
	v_add_f32_e32 v13, v13, v7
	v_add_f32_e32 v13, v13, v32
	v_add_f32_e32 v13, v13, v33
	v_add_f32_e32 v13, v13, v34
	v_add_f32_e32 v13, v13, v36
	v_add_f32_e32 v13, v13, v38
	v_add_f32_e32 v13, v13, v39
	v_sub_f32_e32 v14, v50, v8
	v_add_f32_e32 v13, v13, v44
	v_exp_f32_e32 v40, v14
	v_sub_f32_e32 v14, v51, v8
	v_add_f32_e32 v13, v13, v49
	v_exp_f32_e32 v42, v14
	v_sub_f32_e32 v14, v52, v8
	v_add_f32_e32 v13, v13, v35
	v_exp_f32_e32 v47, v14
	v_sub_f32_e32 v14, v53, v8
	v_add_f32_e32 v13, v13, v37
	v_exp_f32_e32 v50, v14
	v_sub_f32_e32 v14, v54, v8
	v_add_f32_e32 v13, v13, v40
	v_exp_f32_e32 v56, v14
	v_sub_f32_e32 v14, v192, v8
	v_add_f32_e32 v13, v13, v42
	v_exp_f32_e32 v61, v14
	v_sub_f32_e32 v14, v193, v8
	v_add_f32_e32 v13, v13, v47
	v_exp_f32_e32 v41, v14
	v_sub_f32_e32 v14, v194, v8
	v_add_f32_e32 v13, v13, v50
	v_exp_f32_e32 v43, v14
	v_sub_f32_e32 v14, v58, v8
	v_add_f32_e32 v13, v13, v56
	v_exp_f32_e32 v51, v14
	v_sub_f32_e32 v14, v195, v8
	v_add_f32_e32 v13, v13, v61
	v_exp_f32_e32 v53, v14
	v_sub_f32_e32 v14, v196, v8
	v_add_f32_e32 v13, v13, v41
	v_exp_f32_e32 v58, v14
	v_sub_f32_e32 v14, v197, v8
	v_add_f32_e32 v13, v13, v43
	v_exp_f32_e32 v63, v14
	v_sub_f32_e32 v14, v198, v8
	v_add_f32_e32 v13, v13, v51
	v_exp_f32_e32 v71, v14
	v_sub_f32_e32 v14, v199, v8
	v_add_f32_e32 v13, v13, v53
	v_exp_f32_e32 v75, v14
	v_sub_f32_e32 v14, v200, v8
	v_add_f32_e32 v13, v13, v58
	v_exp_f32_e32 v52, v14
	v_sub_f32_e32 v14, v201, v8
	v_add_f32_e32 v13, v13, v63
	v_exp_f32_e32 v54, v14
	v_sub_f32_e32 v14, v202, v8
	v_add_f32_e32 v13, v13, v71
	v_exp_f32_e32 v65, v14
	v_sub_f32_e32 v14, v203, v8
	v_add_f32_e32 v13, v13, v75
	v_exp_f32_e32 v69, v14
	v_sub_f32_e32 v14, v204, v8
	v_add_f32_e32 v13, v13, v52
	v_exp_f32_e32 v72, v14
	v_sub_f32_e32 v14, v205, v8
	v_add_f32_e32 v13, v13, v54
	v_exp_f32_e32 v77, v14
	v_sub_f32_e32 v14, v206, v8
	v_add_f32_e32 v13, v13, v65
	v_exp_f32_e32 v126, v14
	v_sub_f32_e32 v14, v207, v8
	v_add_f32_e32 v13, v13, v69
	v_exp_f32_e32 v129, v14
	v_sub_f32_e32 v14, v208, v8
	v_add_f32_e32 v13, v13, v72
	v_exp_f32_e32 v67, v14
	v_sub_f32_e32 v14, v125, v8
	v_add_f32_e32 v13, v13, v77
	v_exp_f32_e32 v70, v14
	v_sub_f32_e32 v14, v124, v8
	v_add_f32_e32 v13, v13, v126
	v_exp_f32_e32 v80, v14
	v_sub_f32_e32 v14, v123, v8
	v_add_f32_e32 v13, v13, v129
	v_exp_f32_e32 v124, v14
	v_sub_f32_e32 v14, v122, v8
	v_add_f32_e32 v13, v13, v67
	v_exp_f32_e32 v127, v14
	v_sub_f32_e32 v14, v79, v8
	v_add_f32_e32 v13, v13, v70
	v_exp_f32_e32 v131, v14
	v_sub_f32_e32 v14, v78, v8
	v_add_f32_e32 v13, v13, v80
	v_exp_f32_e32 v199, v14
	v_sub_f32_e32 v14, v76, v8
	v_add_f32_e32 v13, v13, v124
	v_exp_f32_e32 v201, v14
	v_sub_f32_e32 v14, v74, v8
	v_add_f32_e32 v13, v13, v127
	v_exp_f32_e32 v121, v14
	v_sub_f32_e32 v14, v73, v8
	v_add_f32_e32 v13, v13, v131
	v_exp_f32_e32 v125, v14
	v_sub_f32_e32 v14, v68, v8
	v_add_f32_e32 v13, v13, v199
	v_exp_f32_e32 v192, v14
	v_sub_f32_e32 v14, v66, v8
	v_add_f32_e32 v13, v13, v201
	v_exp_f32_e32 v196, v14
	v_sub_f32_e32 v14, v64, v8
	v_add_f32_e32 v13, v13, v121
	v_exp_f32_e32 v200, v14
	v_sub_f32_e32 v14, v62, v8
	v_add_f32_e32 v13, v13, v125
	v_exp_f32_e32 v202, v14
	v_sub_f32_e32 v14, v60, v8
	v_add_f32_e32 v13, v13, v192
	v_exp_f32_e32 v203, v14
	v_sub_f32_e32 v14, v57, v8
	v_add_f32_e32 v13, v13, v196
	v_exp_f32_e32 v204, v14
	v_sub_f32_e32 v14, v59, v8
	v_add_f32_e32 v13, v13, v200
	v_exp_f32_e32 v128, v14
	v_sub_f32_e32 v14, v48, v8
	v_add_f32_e32 v13, v13, v202
	v_exp_f32_e32 v130, v14
	v_sub_f32_e32 v14, v55, v8
	v_add_f32_e32 v13, v13, v203
	v_exp_f32_e32 v191, v14
	v_sub_f32_e32 v14, v45, v8
	v_add_f32_e32 v13, v13, v204
	v_exp_f32_e32 v193, v14
	v_sub_f32_e32 v14, v46, v8
	v_add_f32_e32 v13, v13, v128
	v_exp_f32_e32 v194, v14
	v_sub_f32_e32 v14, v27, v8
	v_add_f32_e32 v13, v13, v130
	v_exp_f32_e32 v195, v14
	v_sub_f32_e32 v14, v28, v8
	v_add_f32_e32 v13, v13, v191
	v_exp_f32_e32 v197, v14
	v_sub_f32_e32 v14, v23, v8
	v_add_f32_e32 v13, v13, v193
	v_exp_f32_e32 v198, v14
	v_sub_f32_e32 v14, v24, v8
	v_add_f32_e32 v13, v13, v194
	v_exp_f32_e32 v73, v14
	v_sub_f32_e32 v14, v29, v8
	v_add_f32_e32 v13, v13, v195
	v_exp_f32_e32 v74, v14
	v_sub_f32_e32 v14, v30, v8
	v_add_f32_e32 v13, v13, v197
	v_exp_f32_e32 v76, v14
	v_sub_f32_e32 v14, v25, v8
	v_add_f32_e32 v13, v13, v198
	v_exp_f32_e32 v78, v14
	v_sub_f32_e32 v14, v26, v8
	v_add_f32_e32 v13, v13, v73
	v_exp_f32_e32 v79, v14
	v_sub_f32_e32 v14, v21, v8
	v_add_f32_e32 v13, v13, v74
	v_exp_f32_e32 v120, v14
	v_sub_f32_e32 v14, v22, v8
	v_add_f32_e32 v13, v13, v76
	v_exp_f32_e32 v122, v14
	v_sub_f32_e32 v14, v19, v8
	v_add_f32_e32 v13, v13, v78
	v_exp_f32_e32 v123, v14
	v_sub_f32_e32 v14, v20, v8
	v_add_f32_e32 v13, v13, v79
	v_exp_f32_e32 v55, v14
	v_sub_f32_e32 v14, v17, v8
	v_add_f32_e32 v13, v13, v120
	v_exp_f32_e32 v57, v14
	v_sub_f32_e32 v14, v18, v8
	v_add_f32_e32 v13, v13, v122
	v_exp_f32_e32 v59, v14
	v_sub_f32_e32 v14, v16, v8
	v_add_f32_e32 v13, v13, v123
	v_exp_f32_e32 v60, v14
	v_sub_f32_e32 v12, v12, v8
	v_add_f32_e32 v13, v13, v55
	v_exp_f32_e32 v62, v12
	v_sub_f32_e32 v10, v10, v8
	v_add_f32_e32 v13, v13, v57
	v_exp_f32_e32 v64, v10
	v_sub_f32_e32 v11, v11, v8
	v_add_f32_e32 v13, v13, v59
	v_exp_f32_e32 v66, v11
	v_sub_f32_e32 v9, v9, v8
	v_add_f32_e32 v13, v13, v60
	v_exp_f32_e32 v68, v9
	v_add_f32_e32 v12, v13, v62
	v_add_f32_e32 v10, v12, v64
	v_add_f32_e32 v10, v10, v66
	v_fma_f32 v8, v188, s80, -v8
	v_add_f32_e32 v45, v10, v68
	v_exp_f32_e32 v48, v8
	v_cvt_pk_bf16_f32 v0, v0, v1
	v_cvt_pk_bf16_f32 v1, v2, v3
	v_cvt_pk_bf16_f32 v2, v4, v5
	v_cvt_pk_bf16_f32 v3, v6, v7
	ds_read_b128 v[4:7], v181 offset:36864
	ds_read_b128 v[8:11], v181 offset:53760
	s_waitcnt lgkmcnt(1)
	v_mfma_f32_32x32x16_bf16 v[16:31], v[4:7], v[0:3], 0
	v_cvt_pk_bf16_f32 v220, v32, v33
	v_cvt_pk_bf16_f32 v221, v34, v36
	v_cvt_pk_bf16_f32 v222, v38, v39
	v_cvt_pk_bf16_f32 v223, v44, v49
	ds_read_b128 v[224:227], v181 offset:36896
	ds_read_b128 v[228:231], v181 offset:53792
	v_cvt_pk_bf16_f32 v32, v35, v37
	v_cvt_pk_bf16_f32 v33, v40, v42
	s_waitcnt lgkmcnt(2)
	v_mfma_f32_32x32x16_bf16 v[0:15], v[8:11], v[0:3], 0
	v_cvt_pk_bf16_f32 v34, v47, v50
	v_cvt_pk_bf16_f32 v35, v56, v61
	ds_bpermute_b32 v46, v189, v45
	s_waitcnt lgkmcnt(2)
	v_mfma_f32_32x32x16_bf16 v[16:31], v[224:227], v[220:223], v[16:31]
	s_waitcnt lgkmcnt(1)
	v_mfma_f32_32x32x16_bf16 v[0:15], v[228:231], v[220:223], v[0:15]
	ds_read_b128 v[84:87], v182 offset:36864
	ds_read_b128 v[88:91], v182 offset:53760
	ds_read_b128 v[92:95], v182 offset:36896
	ds_read_b128 v[96:99], v182 offset:53792
	s_waitcnt lgkmcnt(3)
	v_mfma_f32_32x32x16_bf16 v[16:31], v[84:87], v[32:35], v[16:31]
	s_waitcnt lgkmcnt(2)
	v_mfma_f32_32x32x16_bf16 v[0:15], v[88:91], v[32:35], v[0:15]
	v_cvt_pk_bf16_f32 v32, v41, v43
	v_cvt_pk_bf16_f32 v33, v51, v53
	v_cvt_pk_bf16_f32 v34, v58, v63
	v_cvt_pk_bf16_f32 v35, v71, v75
	ds_read_b128 v[84:87], v183 offset:36864
	ds_read_b128 v[88:91], v183 offset:53760
	s_waitcnt lgkmcnt(3)
	v_mfma_f32_32x32x16_bf16 v[16:31], v[92:95], v[32:35], v[16:31]
	s_waitcnt lgkmcnt(2)
	v_mfma_f32_32x32x16_bf16 v[0:15], v[96:99], v[32:35], v[0:15]
	v_cvt_pk_bf16_f32 v32, v52, v54
	v_cvt_pk_bf16_f32 v33, v65, v69
	v_cvt_pk_bf16_f32 v34, v72, v77
	v_cvt_pk_bf16_f32 v35, v126, v129
	ds_read_b128 v[92:95], v183 offset:36896
	ds_read_b128 v[96:99], v183 offset:53792
	s_waitcnt lgkmcnt(3)
	v_mfma_f32_32x32x16_bf16 v[16:31], v[84:87], v[32:35], v[16:31]
	s_waitcnt lgkmcnt(2)
	v_mfma_f32_32x32x16_bf16 v[0:15], v[88:91], v[32:35], v[0:15]
	v_cvt_pk_bf16_f32 v32, v67, v70
	v_cvt_pk_bf16_f32 v33, v80, v124
	v_cvt_pk_bf16_f32 v34, v127, v131
	v_cvt_pk_bf16_f32 v35, v199, v201
	ds_read_b128 v[84:87], v184 offset:36864
	ds_read_b128 v[88:91], v184 offset:53760
	s_waitcnt lgkmcnt(3)
	v_mfma_f32_32x32x16_bf16 v[16:31], v[92:95], v[32:35], v[16:31]
	s_waitcnt lgkmcnt(2)
	v_mfma_f32_32x32x16_bf16 v[0:15], v[96:99], v[32:35], v[0:15]
	v_cvt_pk_bf16_f32 v32, v121, v125
	v_cvt_pk_bf16_f32 v33, v192, v196
	v_cvt_pk_bf16_f32 v34, v200, v202
	v_cvt_pk_bf16_f32 v35, v203, v204
	ds_read_b128 v[92:95], v184 offset:36896
	ds_read_b128 v[96:99], v184 offset:53792
	s_waitcnt lgkmcnt(3)
	v_mfma_f32_32x32x16_bf16 v[16:31], v[84:87], v[32:35], v[16:31]
	s_waitcnt lgkmcnt(2)
	v_mfma_f32_32x32x16_bf16 v[0:15], v[88:91], v[32:35], v[0:15]
	v_cvt_pk_bf16_f32 v32, v128, v130
	v_cvt_pk_bf16_f32 v33, v191, v193
	v_cvt_pk_bf16_f32 v34, v194, v195
	v_cvt_pk_bf16_f32 v35, v197, v198
	ds_read_b128 v[84:87], v185 offset:36864
	ds_read_b128 v[88:91], v185 offset:53760
	s_waitcnt lgkmcnt(3)
	v_mfma_f32_32x32x16_bf16 v[16:31], v[92:95], v[32:35], v[16:31]
	s_waitcnt lgkmcnt(2)
	v_mfma_f32_32x32x16_bf16 v[0:15], v[96:99], v[32:35], v[0:15]
	v_cvt_pk_bf16_f32 v32, v73, v74
	v_cvt_pk_bf16_f32 v33, v76, v78
	v_cvt_pk_bf16_f32 v34, v79, v120
	v_cvt_pk_bf16_f32 v35, v122, v123
	ds_read_b128 v[92:95], v185 offset:36896
	ds_read_b128 v[96:99], v185 offset:53792
	s_waitcnt lgkmcnt(3)
	v_mfma_f32_32x32x16_bf16 v[16:31], v[84:87], v[32:35], v[16:31]
	s_waitcnt lgkmcnt(2)
	v_mfma_f32_32x32x16_bf16 v[0:15], v[88:91], v[32:35], v[0:15]
	v_cvt_pk_bf16_f32 v32, v55, v57
	v_cvt_pk_bf16_f32 v33, v59, v60
	v_cvt_pk_bf16_f32 v34, v62, v64
	v_cvt_pk_bf16_f32 v35, v66, v68
	s_waitcnt lgkmcnt(1)
	v_mfma_f32_32x32x16_bf16 v[16:31], v[92:95], v[32:35], v[16:31]
	s_waitcnt lgkmcnt(0)
	v_mfma_f32_32x32x16_bf16 v[0:15], v[96:99], v[32:35], v[0:15]
	v_add_f32_e32 v32, v45, v46
	v_add_f32_e32 v32, v48, v32
	v_div_scale_f32 v33, s[80:81], v32, v32, 1.0
	v_rcp_f32_e32 v34, v33
	v_readlane_b32 s80, v253, 57
	v_readlane_b32 s81, v253, 58
	v_fma_f32 v35, -v33, v34, 1.0
	v_fmac_f32_e32 v34, v35, v34
	v_div_scale_f32 v35, vcc, 1.0, v32, 1.0
	v_mul_f32_e32 v36, v35, v34
	v_fma_f32 v37, -v33, v36, v35
	v_fmac_f32_e32 v36, v37, v34
	v_fma_f32 v33, -v33, v36, v35
	v_div_fmas_f32 v33, v33, v34, v36
	v_div_fixup_f32 v34, v33, v32, 1.0
	v_lshrrev_b64 v[32:33], 2, v[162:163]
	v_and_b32_e32 v33, 0x3ffff, v33
	v_and_b32_e32 v32, 0xffffffe0, v32
	v_lshlrev_b32_e32 v35, 6, v162
	v_lshlrev_b32_e32 v37, 2, v162
	v_lshl_add_u64 v[32:33], v[32:33], 0, s[34:35]
	v_and_b32_e32 v35, 0x3c0, v35
	v_lshlrev_b32_e32 v36, 7, v162
	v_and_b32_e32 v37, 32, v37
	v_and_b32_e32 v36, 0x3800, v36
	v_lshlrev_b64 v[32:33], 14, v[32:33]
	v_mul_f32_e32 v16, v34, v16
	v_mul_f32_e32 v17, v34, v17
	v_or3_b32 v39, v137, v35, v37
	v_lshl_add_u64 v[32:33], s[80:81], 0, v[32:33]
	v_cvt_pk_bf16_f32 v16, v16, v17
	v_mul_f32_e32 v17, v34, v18
	v_mul_f32_e32 v18, v34, v19
	v_or_b32_e32 v80, v39, v36
	v_or_b32_e32 v38, 0x400, v36
	v_cvt_pk_bf16_f32 v17, v17, v18
	v_lshl_add_u64 v[18:19], v[32:33], 0, v[80:81]
	v_mul_f32_e32 v0, v34, v0
	v_mul_f32_e32 v1, v34, v1
	global_store_dwordx2 v[18:19], v[16:17], off
	v_cvt_pk_bf16_f32 v0, v0, v1
	v_mul_f32_e32 v1, v34, v2
	v_mul_f32_e32 v2, v34, v3
	v_or_b32_e32 v80, v39, v38
	v_cvt_pk_bf16_f32 v1, v1, v2
	v_lshl_add_u64 v[2:3], v[32:33], 0, v[80:81]
	global_store_dwordx2 v[2:3], v[0:1], off
	v_mul_f32_e32 v0, v34, v20
	v_mul_f32_e32 v1, v34, v21
	v_or3_b32 v16, v165, v35, v37
	v_cvt_pk_bf16_f32 v0, v0, v1
	v_mul_f32_e32 v1, v34, v22
	v_mul_f32_e32 v2, v34, v23
	v_or_b32_e32 v80, v16, v36
	v_cvt_pk_bf16_f32 v1, v1, v2
	v_lshl_add_u64 v[2:3], v[32:33], 0, v[80:81]
	global_store_dwordx2 v[2:3], v[0:1], off
	v_mul_f32_e32 v0, v34, v4
	v_mul_f32_e32 v1, v34, v5
	v_cvt_pk_bf16_f32 v0, v0, v1
	v_mul_f32_e32 v1, v34, v6
	v_mul_f32_e32 v2, v34, v7
	v_or_b32_e32 v80, v16, v38
	v_cvt_pk_bf16_f32 v1, v1, v2
	v_lshl_add_u64 v[2:3], v[32:33], 0, v[80:81]
	global_store_dwordx2 v[2:3], v[0:1], off
	v_mul_f32_e32 v0, v34, v24
	v_mul_f32_e32 v1, v34, v25
	v_bitop3_b32 v4, v166, v37, v35 bitop3:0x36
	v_cvt_pk_bf16_f32 v0, v0, v1
	v_mul_f32_e32 v1, v34, v26
	v_mul_f32_e32 v2, v34, v27
	v_or_b32_e32 v80, v4, v36
	v_cvt_pk_bf16_f32 v1, v1, v2
	v_lshl_add_u64 v[2:3], v[32:33], 0, v[80:81]
	global_store_dwordx2 v[2:3], v[0:1], off
	v_mul_f32_e32 v0, v34, v8
	v_mul_f32_e32 v1, v34, v9
	v_cvt_pk_bf16_f32 v0, v0, v1
	v_mul_f32_e32 v1, v34, v10
	v_mul_f32_e32 v2, v34, v11
	v_or_b32_e32 v80, v4, v38
	v_cvt_pk_bf16_f32 v1, v1, v2
	v_lshl_add_u64 v[2:3], v[32:33], 0, v[80:81]
	global_store_dwordx2 v[2:3], v[0:1], off
	v_mul_f32_e32 v0, v34, v28
	v_mul_f32_e32 v1, v34, v29
	v_bitop3_b32 v4, v167, v37, v35 bitop3:0x36
	v_cvt_pk_bf16_f32 v0, v0, v1
	v_mul_f32_e32 v1, v34, v30
	v_mul_f32_e32 v2, v34, v31
	v_or_b32_e32 v80, v4, v36
	v_cvt_pk_bf16_f32 v1, v1, v2
	v_lshl_add_u64 v[2:3], v[32:33], 0, v[80:81]
	global_store_dwordx2 v[2:3], v[0:1], off
	v_mul_f32_e32 v0, v34, v12
	v_mul_f32_e32 v1, v34, v13
	v_cvt_pk_bf16_f32 v0, v0, v1
	v_mul_f32_e32 v1, v34, v14
	v_mul_f32_e32 v2, v34, v15
	v_or_b32_e32 v80, v4, v38
	v_cvt_pk_bf16_f32 v1, v1, v2
	v_lshl_add_u64 v[2:3], v[32:33], 0, v[80:81]
	global_store_dwordx2 v[2:3], v[0:1], off
	ds_read_b128 v[0:3], v177
	ds_read_b128 v[4:7], v177 offset:32
	s_waitcnt lgkmcnt(1)
	v_mfma_f32_32x32x16_bf16 v[64:79], v[0:3], v[116:119], 0
	ds_read_b128 v[0:3], v177 offset:64
	s_waitcnt lgkmcnt(1)
	v_mfma_f32_32x32x16_bf16 v[64:79], v[4:7], v[112:115], v[64:79]
	s_waitcnt lgkmcnt(0)
	v_mfma_f32_32x32x16_bf16 v[64:79], v[0:3], v[108:111], v[64:79]
	ds_read_b128 v[0:3], v177 offset:96
	s_waitcnt lgkmcnt(0)
	v_mfma_f32_32x32x16_bf16 v[64:79], v[0:3], v[104:107], v[64:79]
	ds_read_b128 v[0:3], v178
	ds_read_b128 v[4:7], v178 offset:32
	s_waitcnt lgkmcnt(1)
	v_mfma_f32_32x32x16_bf16 v[48:63], v[0:3], v[116:119], 0
	ds_read_b128 v[0:3], v178 offset:64
	s_nop 6
	v_mul_f32_e32 v66, 0x3e38aa3b, v66
	v_mul_f32_e32 v64, 0x3e38aa3b, v64
	v_mul_f32_e32 v65, 0x3e38aa3b, v65
	v_cndmask_b32_e64 v64, v239, v64, s[82:83]
	v_cndmask_b32_e64 v80, v239, v65, s[84:85]
	v_max3_f32 v65, v190, v64, v80
	s_waitcnt lgkmcnt(1)
	v_mfma_f32_32x32x16_bf16 v[48:63], v[4:7], v[112:115], v[48:63]
	s_waitcnt lgkmcnt(0)
	v_mfma_f32_32x32x16_bf16 v[48:63], v[0:3], v[108:111], v[48:63]
	ds_read_b128 v[0:3], v178 offset:96
	s_waitcnt lgkmcnt(0)
	v_mfma_f32_32x32x16_bf16 v[48:63], v[0:3], v[104:107], v[48:63]
	ds_read_b128 v[0:3], v179
	ds_read_b128 v[4:7], v179 offset:32
	s_waitcnt lgkmcnt(1)
	v_mfma_f32_32x32x16_bf16 v[32:47], v[0:3], v[116:119], 0
	ds_read_b128 v[0:3], v179 offset:64
	s_nop 6
	v_mul_f32_e32 v48, 0x3e38aa3b, v48
	s_waitcnt lgkmcnt(1)
	v_mfma_f32_32x32x16_bf16 v[32:47], v[4:7], v[112:115], v[32:47]
	s_waitcnt lgkmcnt(0)
	v_mfma_f32_32x32x16_bf16 v[32:47], v[0:3], v[108:111], v[32:47]
	ds_read_b128 v[0:3], v179 offset:96
	s_waitcnt lgkmcnt(0)
	v_mfma_f32_32x32x16_bf16 v[32:47], v[0:3], v[104:107], v[32:47]
	ds_read_b128 v[0:3], v180
	ds_read_b128 v[16:19], v180 offset:32
	s_waitcnt lgkmcnt(1)
	v_mfma_f32_32x32x16_bf16 v[0:15], v[0:3], v[116:119], 0
	s_nop 7
	v_mul_f32_e32 v32, 0x3e38aa3b, v32
	s_waitcnt lgkmcnt(0)
	v_mfma_f32_32x32x16_bf16 v[0:15], v[16:19], v[112:115], v[0:15]
	ds_read_b128 v[16:19], v180 offset:64
	s_waitcnt lgkmcnt(0)
	v_mfma_f32_32x32x16_bf16 v[0:15], v[16:19], v[108:111], v[0:15]
	ds_read_b128 v[16:19], v180 offset:96
	s_waitcnt lgkmcnt(0)
	v_mfma_f32_32x32x16_bf16 v[0:15], v[16:19], v[104:107], v[0:15]
	ds_read_b128 v[16:19], v186
	ds_read_b128 v[120:123], v186 offset:32
	s_waitcnt lgkmcnt(1)
	v_mfma_f32_32x32x16_bf16 v[16:31], v[16:19], v[116:119], 0
	s_waitcnt lgkmcnt(0)
	v_mfma_f32_32x32x16_bf16 v[16:31], v[120:123], v[112:115], v[16:31]
	ds_read_b128 v[112:115], v186 offset:64
	v_cndmask_b32_e64 v122, v239, v32, s[16:17]
	v_mul_f32_e32 v32, 0x3e38aa3b, v33
	v_mul_f32_e32 v33, 0x3e38aa3b, v34
	v_cndmask_b32_e64 v124, v239, v33, s[16:17]
	v_mul_f32_e32 v33, 0x3e38aa3b, v35
	v_cndmask_b32_e64 v125, v239, v33, s[16:17]
	s_waitcnt lgkmcnt(0)
	v_mfma_f32_32x32x16_bf16 v[16:31], v[112:115], v[108:111], v[16:31]
	ds_read_b128 v[108:111], v186 offset:96
	v_cndmask_b32_e64 v112, v239, v48, s[16:17]
	v_mul_f32_e32 v48, 0x3e38aa3b, v49
	v_mul_f32_e32 v49, 0x3e38aa3b, v50
	v_cndmask_b32_e64 v50, v239, v49, s[16:17]
	v_mul_f32_e32 v49, 0x3e38aa3b, v51
	v_cndmask_b32_e64 v51, v239, v49, s[16:17]
	s_waitcnt lgkmcnt(0)
	v_mfma_f32_32x32x16_bf16 v[16:31], v[108:111], v[104:107], v[16:31]
	v_cndmask_b32_e64 v104, v239, v66, s[86:87]
	v_mul_f32_e32 v66, 0x3e38aa3b, v67
	v_cndmask_b32_e64 v105, v239, v66, s[88:89]
	v_mul_f32_e32 v66, 0x3e38aa3b, v68
	v_cndmask_b32_e64 v106, v239, v66, s[90:91]
	v_mul_f32_e32 v66, 0x3e38aa3b, v69
	v_cndmask_b32_e64 v69, v239, v66, s[92:93]
	v_mul_f32_e32 v66, 0x3e38aa3b, v70
	v_cndmask_b32_e64 v107, v239, v66, s[94:95]
	v_mul_f32_e32 v66, 0x3e38aa3b, v71
	v_cndmask_b32_e64 v71, v239, v66, s[96:97]
	v_mul_f32_e32 v66, 0x3e38aa3b, v72
	v_cndmask_b32_e64 v72, v239, v66, s[28:29]
	v_mul_f32_e32 v66, 0x3e38aa3b, v73
	v_cndmask_b32_e64 v108, v239, v66, s[4:5]
	v_mul_f32_e32 v66, 0x3e38aa3b, v74
	v_max3_f32 v65, v65, v104, v105
	v_cndmask_b32_e64 v74, v239, v66, s[6:7]
	v_mul_f32_e32 v66, 0x3e38aa3b, v75
	v_max3_f32 v65, v65, v106, v69
	v_cndmask_b32_e64 v109, v239, v66, s[8:9]
	v_mul_f32_e32 v66, 0x3e38aa3b, v76
	v_mul_f32_e32 v49, 0x3e38aa3b, v52
	v_max3_f32 v65, v65, v107, v71
	v_cndmask_b32_e64 v110, v239, v66, s[10:11]
	v_mul_f32_e32 v66, 0x3e38aa3b, v77
	v_cndmask_b32_e64 v52, v239, v49, s[16:17]
	v_mul_f32_e32 v49, 0x3e38aa3b, v53
	v_max3_f32 v65, v65, v72, v108
	v_cndmask_b32_e64 v77, v239, v66, s[12:13]
	v_mul_f32_e32 v66, 0x3e38aa3b, v78
	v_cndmask_b32_e64 v53, v239, v49, s[16:17]
	v_mul_f32_e32 v49, 0x3e38aa3b, v54
	v_max3_f32 v65, v65, v74, v109
	v_cndmask_b32_e64 v111, v239, v66, s[14:15]
	v_mul_f32_e32 v66, 0x3e38aa3b, v79
	v_cndmask_b32_e64 v54, v239, v49, s[16:17]
	v_mul_f32_e32 v49, 0x3e38aa3b, v55
	v_max3_f32 v65, v65, v110, v77
	v_cndmask_b32_e64 v79, v239, v66, s[18:19]
	v_cndmask_b32_e64 v114, v239, v49, s[16:17]
	v_mul_f32_e32 v49, 0x3e38aa3b, v56
	v_max3_f32 v65, v65, v111, v79
	v_cndmask_b32_e64 v113, v239, v48, s[16:17]
	v_cndmask_b32_e64 v115, v239, v49, s[16:17]
	v_mul_f32_e32 v49, 0x3e38aa3b, v57
	v_max3_f32 v48, v65, v112, v113
	v_cndmask_b32_e64 v57, v239, v49, s[16:17]
	v_mul_f32_e32 v49, 0x3e38aa3b, v58
	v_max3_f32 v48, v48, v50, v51
	v_cndmask_b32_e64 v116, v239, v49, s[16:17]
	v_mul_f32_e32 v49, 0x3e38aa3b, v59
	v_max3_f32 v48, v48, v52, v53
	v_cndmask_b32_e64 v117, v239, v49, s[16:17]
	v_mul_f32_e32 v49, 0x3e38aa3b, v60
	v_mul_f32_e32 v33, 0x3e38aa3b, v36
	v_max3_f32 v48, v48, v54, v114
	v_cndmask_b32_e64 v118, v239, v49, s[16:17]
	v_mul_f32_e32 v49, 0x3e38aa3b, v61
	v_cndmask_b32_e64 v126, v239, v33, s[16:17]
	v_mul_f32_e32 v33, 0x3e38aa3b, v37
	v_max3_f32 v48, v48, v115, v57
	v_cndmask_b32_e64 v119, v239, v49, s[16:17]
	v_mul_f32_e32 v49, 0x3e38aa3b, v62
	v_cndmask_b32_e64 v127, v239, v33, s[16:17]
	v_mul_f32_e32 v33, 0x3e38aa3b, v38
	v_max3_f32 v48, v48, v116, v117
	v_cndmask_b32_e64 v120, v239, v49, s[16:17]
	v_mul_f32_e32 v49, 0x3e38aa3b, v63
	v_cndmask_b32_e64 v128, v239, v33, s[16:17]
	v_mul_f32_e32 v33, 0x3e38aa3b, v39
	v_max3_f32 v48, v48, v118, v119
	v_cndmask_b32_e64 v121, v239, v49, s[16:17]
	v_cndmask_b32_e64 v78, v239, v33, s[16:17]
	v_mul_f32_e32 v33, 0x3e38aa3b, v40
	v_max3_f32 v48, v48, v120, v121
	v_cndmask_b32_e64 v123, v239, v32, s[16:17]
	v_cndmask_b32_e64 v67, v239, v33, s[16:17]
	v_mul_f32_e32 v33, 0x3e38aa3b, v41
	v_max3_f32 v32, v48, v122, v123
	v_cndmask_b32_e64 v70, v239, v33, s[16:17]
	v_mul_f32_e32 v33, 0x3e38aa3b, v42
	v_max3_f32 v32, v32, v124, v125
	v_cndmask_b32_e64 v76, v239, v33, s[16:17]
	v_mul_f32_e32 v33, 0x3e38aa3b, v43
	v_max3_f32 v32, v32, v126, v127
	v_cndmask_b32_e64 v75, v239, v33, s[16:17]
	v_mul_f32_e32 v33, 0x3e38aa3b, v44
	v_max3_f32 v32, v32, v128, v78
	v_cndmask_b32_e64 v73, v239, v33, s[16:17]
	v_mul_f32_e32 v33, 0x3e38aa3b, v45
	v_max3_f32 v32, v32, v67, v70
	v_cndmask_b32_e64 v68, v239, v33, s[16:17]
	v_mul_f32_e32 v33, 0x3e38aa3b, v46
	v_max3_f32 v32, v32, v76, v75
	v_cndmask_b32_e64 v66, v239, v33, s[16:17]
	v_mul_f32_e32 v33, 0x3e38aa3b, v47
	v_max3_f32 v32, v32, v73, v68
	v_cndmask_b32_e64 v65, v239, v33, s[16:17]
	v_max3_f32 v32, v32, v66, v65
	v_mul_f32_e32 v33, 0x3e38aa3b, v0
	v_mul_f32_e32 v34, 0x3e38aa3b, v1
	v_mul_f32_e32 v16, 0x3e38aa3b, v16
	v_max3_f32 v32, v32, v33, v34
	v_mul_f32_e32 v33, 0x3e38aa3b, v2
	v_mul_f32_e32 v34, 0x3e38aa3b, v3
	v_cndmask_b32_e64 v46, v16, v239, s[52:53]
	v_mul_f32_e32 v16, 0x3e38aa3b, v17
	v_mul_f32_e32 v17, 0x3e38aa3b, v18
	v_max3_f32 v32, v32, v33, v34
	v_mul_f32_e32 v33, 0x3e38aa3b, v4
	v_mul_f32_e32 v34, 0x3e38aa3b, v5
	v_cndmask_b32_e64 v48, v17, v239, s[48:49]
	v_mul_f32_e32 v17, 0x3e38aa3b, v19
	v_max3_f32 v32, v32, v33, v34
	v_mul_f32_e32 v33, 0x3e38aa3b, v6
	v_mul_f32_e32 v34, 0x3e38aa3b, v7
	v_cndmask_b32_e64 v56, v17, v239, s[56:57]
	v_mul_f32_e32 v17, 0x3e38aa3b, v20
	v_max3_f32 v32, v32, v33, v34
	v_mul_f32_e32 v33, 0x3e38aa3b, v8
	v_mul_f32_e32 v34, 0x3e38aa3b, v9
	v_cndmask_b32_e64 v58, v17, v239, s[38:39]
	v_mul_f32_e32 v17, 0x3e38aa3b, v21
	v_max3_f32 v32, v32, v33, v34
	v_mul_f32_e32 v33, 0x3e38aa3b, v10
	v_mul_f32_e32 v34, 0x3e38aa3b, v11
	v_cndmask_b32_e64 v59, v17, v239, s[2:3]
	v_mul_f32_e32 v17, 0x3e38aa3b, v22
	v_max3_f32 v32, v32, v33, v34
	v_mul_f32_e32 v33, 0x3e38aa3b, v12
	v_mul_f32_e32 v34, 0x3e38aa3b, v13
	v_cndmask_b32_e64 v61, v17, v239, s[40:41]
	v_mul_f32_e32 v17, 0x3e38aa3b, v23
	v_max3_f32 v32, v32, v33, v34
	v_mul_f32_e32 v33, 0x3e38aa3b, v14
	v_mul_f32_e32 v34, 0x3e38aa3b, v15
	v_cndmask_b32_e64 v63, v17, v239, s[42:43]
	v_mul_f32_e32 v17, 0x3e38aa3b, v24
	v_max3_f32 v32, v32, v33, v34
	v_cndmask_b32_e64 v47, v239, v16, s[0:1]
	v_cndmask_b32_e64 v24, v17, v239, s[44:45]
	v_mul_f32_e32 v17, 0x3e38aa3b, v25
	v_max3_f32 v16, v32, v46, v47
	v_cndmask_b32_e64 v25, v17, v239, s[68:69]
	v_mul_f32_e32 v17, 0x3e38aa3b, v26
	v_max3_f32 v16, v16, v48, v56
	v_cndmask_b32_e64 v26, v17, v239, s[70:71]
	v_mul_f32_e32 v17, 0x3e38aa3b, v27
	v_max3_f32 v16, v16, v58, v59
	v_cndmask_b32_e64 v27, v17, v239, s[72:73]
	v_mul_f32_e32 v17, 0x3e38aa3b, v28
	v_max3_f32 v16, v16, v61, v63
	v_cndmask_b32_e64 v28, v17, v239, s[74:75]
	v_mul_f32_e32 v17, 0x3e38aa3b, v29
	v_max3_f32 v16, v16, v24, v25
	v_cndmask_b32_e64 v29, v17, v239, s[76:77]
	v_mul_f32_e32 v17, 0x3e38aa3b, v30
	v_max3_f32 v16, v16, v26, v27
	v_cndmask_b32_e64 v30, v17, v239, s[78:79]
	v_mul_f32_e32 v17, 0x3e38aa3b, v31
	v_max3_f32 v16, v16, v28, v29
	v_cndmask_b32_e64 v31, v17, v239, s[36:37]
	v_max3_f32 v16, v16, v30, v31
	ds_bpermute_b32 v17, v189, v16
	s_mov_b32 s0, 0x3e38aa3b
	s_waitcnt lgkmcnt(0)
	v_max_f32_e32 v17, v17, v17
	v_max_f32_e32 v130, v16, v17
	v_sub_f32_e32 v16, v64, v130
	v_exp_f32_e32 v16, v16
	v_sub_f32_e32 v17, v80, v130
	v_exp_f32_e32 v17, v17
	v_sub_f32_e32 v36, v109, v130
	v_add_f32_e32 v18, 0, v16
	v_exp_f32_e32 v36, v36
	v_add_f32_e32 v19, v18, v17
	v_sub_f32_e32 v18, v104, v130
	v_exp_f32_e32 v18, v18
	v_sub_f32_e32 v37, v110, v130
	v_exp_f32_e32 v38, v37
	v_sub_f32_e32 v37, v77, v130
	v_add_f32_e32 v20, v19, v18
	v_sub_f32_e32 v19, v105, v130
	v_exp_f32_e32 v19, v19
	v_exp_f32_e32 v39, v37
	v_sub_f32_e32 v37, v111, v130
	v_exp_f32_e32 v44, v37
	v_add_f32_e32 v21, v20, v19
	v_sub_f32_e32 v20, v106, v130
	v_exp_f32_e32 v20, v20
	v_sub_f32_e32 v37, v79, v130
	v_exp_f32_e32 v49, v37
	v_sub_f32_e32 v42, v51, v130
	v_add_f32_e32 v22, v21, v20
	v_sub_f32_e32 v21, v69, v130
	v_exp_f32_e32 v21, v21
	v_exp_f32_e32 v42, v42
	v_sub_f32_e32 v43, v52, v130
	v_exp_f32_e32 v45, v43
	v_add_f32_e32 v23, v22, v21
	v_sub_f32_e32 v22, v107, v130
	v_exp_f32_e32 v22, v22
	v_sub_f32_e32 v43, v53, v130
	v_sub_f32_e32 v53, v117, v130
	v_exp_f32_e32 v53, v53
	v_add_f32_e32 v32, v23, v22
	v_sub_f32_e32 v23, v71, v130
	v_exp_f32_e32 v23, v23
	v_sub_f32_e32 v80, v128, v130
	v_exp_f32_e32 v109, v80
	v_sub_f32_e32 v78, v78, v130
	v_add_f32_e32 v33, v32, v23
	v_sub_f32_e32 v32, v72, v130
	v_exp_f32_e32 v32, v32
	v_sub_f32_e32 v67, v67, v130
	v_exp_f32_e32 v67, v67
	v_sub_f32_e32 v70, v70, v130
	v_add_f32_e32 v34, v33, v32
	v_sub_f32_e32 v33, v108, v130
	v_exp_f32_e32 v33, v33
	v_exp_f32_e32 v70, v70
	v_sub_f32_e32 v76, v76, v130
	v_sub_f32_e32 v75, v75, v130
	v_add_f32_e32 v35, v34, v33
	v_sub_f32_e32 v34, v74, v130
	v_exp_f32_e32 v34, v34
	v_exp_f32_e32 v107, v75
	v_sub_f32_e32 v73, v73, v130
	v_exp_f32_e32 v111, v73
	v_add_f32_e32 v35, v35, v34
	v_add_f32_e32 v35, v35, v36
	v_add_f32_e32 v35, v35, v38
	v_add_f32_e32 v35, v35, v39
	v_add_f32_e32 v35, v35, v44
	v_add_f32_e32 v37, v35, v49
	v_sub_f32_e32 v35, v112, v130
	v_exp_f32_e32 v35, v35
	v_exp_f32_e32 v112, v78
	v_sub_f32_e32 v68, v68, v130
	v_sub_f32_e32 v66, v66, v130
	v_add_f32_e32 v40, v37, v35
	v_sub_f32_e32 v37, v113, v130
	v_exp_f32_e32 v37, v37
	v_sub_f32_e32 v65, v65, v130
	v_fma_f32 v0, v0, s0, -v130
	v_exp_f32_e32 v104, v0
	v_add_f32_e32 v41, v40, v37
	v_sub_f32_e32 v40, v50, v130
	v_exp_f32_e32 v40, v40
	v_exp_f32_e32 v50, v43
	v_sub_f32_e32 v43, v54, v130
	v_exp_f32_e32 v55, v43
	v_add_f32_e32 v41, v41, v40
	v_sub_f32_e32 v43, v114, v130
	v_add_f32_e32 v41, v41, v42
	v_exp_f32_e32 v60, v43
	v_add_f32_e32 v41, v41, v45
	v_add_f32_e32 v41, v41, v50
	v_add_f32_e32 v41, v41, v55
	v_add_f32_e32 v43, v41, v60
	v_sub_f32_e32 v41, v115, v130
	v_exp_f32_e32 v41, v41
	v_sub_f32_e32 v54, v118, v130
	v_exp_f32_e32 v114, v68
	v_fma_f32 v1, v1, s0, -v130
	v_add_f32_e32 v51, v43, v41
	v_sub_f32_e32 v43, v57, v130
	v_exp_f32_e32 v43, v43
	v_exp_f32_e32 v57, v54
	v_sub_f32_e32 v54, v119, v130
	v_exp_f32_e32 v62, v54
	v_add_f32_e32 v52, v51, v43
	v_sub_f32_e32 v51, v116, v130
	v_exp_f32_e32 v51, v51
	v_sub_f32_e32 v54, v120, v130
	v_exp_f32_e32 v71, v54
	v_sub_f32_e32 v54, v121, v130
	v_add_f32_e32 v52, v52, v51
	v_add_f32_e32 v52, v52, v53
	v_exp_f32_e32 v74, v54
	v_add_f32_e32 v52, v52, v57
	v_add_f32_e32 v52, v52, v62
	v_add_f32_e32 v52, v52, v71
	v_add_f32_e32 v54, v52, v74
	v_sub_f32_e32 v52, v122, v130
	v_exp_f32_e32 v52, v52
	v_exp_f32_e32 v110, v1
	v_fma_f32 v1, v2, s0, -v130
	v_exp_f32_e32 v117, v1
	v_add_f32_e32 v64, v54, v52
	v_sub_f32_e32 v54, v123, v130
	v_exp_f32_e32 v54, v54
	v_exp_f32_e32 v123, v66
	v_fma_f32 v1, v3, s0, -v130
	v_exp_f32_e32 v121, v1
	v_add_f32_e32 v69, v64, v54
	v_sub_f32_e32 v64, v124, v130
	v_exp_f32_e32 v64, v64
	v_fma_f32 v1, v4, s0, -v130
	v_add_f32_e32 v72, v69, v64
	v_sub_f32_e32 v69, v125, v130
	v_exp_f32_e32 v69, v69
	v_exp_f32_e32 v125, v1
	v_fma_f32 v1, v5, s0, -v130
	v_add_f32_e32 v77, v72, v69
	v_sub_f32_e32 v72, v126, v130
	v_exp_f32_e32 v72, v72
	v_exp_f32_e32 v126, v65
	v_add_f32_e32 v79, v77, v72
	v_sub_f32_e32 v77, v127, v130
	v_exp_f32_e32 v77, v77
	v_exp_f32_e32 v127, v1
	v_fma_f32 v1, v6, s0, -v130
	v_exp_f32_e32 v128, v1
	v_add_f32_e32 v79, v79, v77
	v_add_f32_e32 v79, v79, v109
	v_add_f32_e32 v78, v79, v112
	v_exp_f32_e32 v79, v76
	v_add_f32_e32 v78, v78, v67
	v_add_f32_e32 v78, v78, v70
	v_fma_f32 v1, v7, s0, -v130
	v_add_f32_e32 v76, v78, v79
	v_add_f32_e32 v75, v76, v107
	v_add_f32_e32 v73, v75, v111
	v_add_f32_e32 v68, v73, v114
	v_add_f32_e32 v66, v68, v123
	v_add_f32_e32 v65, v66, v126
	v_add_f32_e32 v0, v65, v104
	v_add_f32_e32 v0, v0, v110
	v_add_f32_e32 v0, v0, v117
	v_add_f32_e32 v0, v0, v121
	v_exp_f32_e32 v129, v1
	v_fma_f32 v1, v8, s0, -v130
	v_add_f32_e32 v0, v0, v125
	v_exp_f32_e32 v113, v1
	v_fma_f32 v1, v9, s0, -v130
	v_add_f32_e32 v0, v0, v127
	v_exp_f32_e32 v115, v1
	v_fma_f32 v1, v10, s0, -v130
	v_add_f32_e32 v0, v0, v128
	v_exp_f32_e32 v116, v1
	v_fma_f32 v1, v11, s0, -v130
	v_add_f32_e32 v0, v0, v129
	v_exp_f32_e32 v118, v1
	v_fma_f32 v1, v12, s0, -v130
	v_add_f32_e32 v0, v0, v113
	v_exp_f32_e32 v119, v1
	v_fma_f32 v1, v13, s0, -v130
	v_add_f32_e32 v0, v0, v115
	v_exp_f32_e32 v120, v1
	v_fma_f32 v1, v14, s0, -v130
	v_add_f32_e32 v0, v0, v116
	v_exp_f32_e32 v122, v1
	v_fma_f32 v1, v15, s0, -v130
	v_add_f32_e32 v0, v0, v118
	v_exp_f32_e32 v124, v1
	v_sub_f32_e32 v1, v46, v130
	v_add_f32_e32 v0, v0, v119
	v_exp_f32_e32 v73, v1
	v_sub_f32_e32 v1, v47, v130
	v_add_f32_e32 v0, v0, v120
	v_exp_f32_e32 v75, v1
	v_sub_f32_e32 v1, v48, v130
	v_add_f32_e32 v0, v0, v122
	v_exp_f32_e32 v76, v1
	v_sub_f32_e32 v1, v56, v130
	v_add_f32_e32 v0, v0, v124
	v_exp_f32_e32 v78, v1
	v_sub_f32_e32 v1, v58, v130
	v_add_f32_e32 v0, v0, v73
	v_exp_f32_e32 v80, v1
	v_sub_f32_e32 v1, v59, v130
	v_add_f32_e32 v0, v0, v75
	v_exp_f32_e32 v105, v1
	v_sub_f32_e32 v1, v61, v130
	v_add_f32_e32 v0, v0, v76
	v_exp_f32_e32 v106, v1
	v_sub_f32_e32 v1, v63, v130
	v_add_f32_e32 v0, v0, v78
	v_exp_f32_e32 v108, v1
	v_sub_f32_e32 v1, v24, v130
	v_add_f32_e32 v0, v0, v80
	v_exp_f32_e32 v56, v1
	v_sub_f32_e32 v1, v25, v130
	v_add_f32_e32 v0, v0, v105
	v_exp_f32_e32 v58, v1
	v_sub_f32_e32 v1, v26, v130
	v_add_f32_e32 v0, v0, v106
	v_exp_f32_e32 v59, v1
	v_sub_f32_e32 v1, v27, v130
	v_add_f32_e32 v0, v0, v108
	v_exp_f32_e32 v61, v1
	v_sub_f32_e32 v1, v28, v130
	v_add_f32_e32 v0, v0, v56
	v_exp_f32_e32 v63, v1
	v_sub_f32_e32 v1, v29, v130
	v_add_f32_e32 v0, v0, v58
	v_exp_f32_e32 v65, v1
	v_sub_f32_e32 v1, v30, v130
	v_add_f32_e32 v0, v0, v59
	v_exp_f32_e32 v66, v1
	v_sub_f32_e32 v1, v31, v130
	v_add_f32_e32 v0, v0, v61
	v_exp_f32_e32 v68, v1
	v_add_f32_e32 v0, v0, v63
	v_add_f32_e32 v0, v0, v65
	v_add_f32_e32 v0, v0, v66
	s_mov_b32 s0, 0x3fb8aa3b
	v_add_f32_e32 v46, v0, v68
	v_fma_f32 v0, v188, s0, -v130
	v_exp_f32_e32 v48, v0
	v_cvt_pk_bf16_f32 v0, v16, v17
	v_cvt_pk_bf16_f32 v1, v18, v19
	v_cvt_pk_bf16_f32 v2, v20, v21
	v_cvt_pk_bf16_f32 v3, v22, v23
	ds_read_b128 v[4:7], v182 offset:36864
	ds_read_b128 v[8:11], v182 offset:53760
	s_waitcnt lgkmcnt(1)
	v_mfma_f32_32x32x16_bf16 v[16:31], v[4:7], v[0:3], 0
	ds_bpermute_b32 v47, v189, v46
	v_cvt_pk_bf16_f32 v188, v32, v33
	v_cvt_pk_bf16_f32 v189, v34, v36
	v_cvt_pk_bf16_f32 v190, v38, v39
	v_cvt_pk_bf16_f32 v191, v44, v49
	ds_read_b128 v[192:195], v182 offset:36896
	ds_read_b128 v[196:199], v182 offset:53792
	v_cvt_pk_bf16_f32 v32, v35, v37
	s_waitcnt lgkmcnt(3)
	v_mfma_f32_32x32x16_bf16 v[0:15], v[8:11], v[0:3], 0
	v_cvt_pk_bf16_f32 v33, v40, v42
	v_cvt_pk_bf16_f32 v34, v45, v50
	v_cvt_pk_bf16_f32 v35, v55, v60
	s_waitcnt lgkmcnt(1)
	v_mfma_f32_32x32x16_bf16 v[16:31], v[192:195], v[188:191], v[16:31]
	s_waitcnt lgkmcnt(0)
	v_mfma_f32_32x32x16_bf16 v[0:15], v[196:199], v[188:191], v[0:15]
	ds_read_b128 v[84:87], v183 offset:36864
	ds_read_b128 v[88:91], v183 offset:53760
	ds_read_b128 v[92:95], v183 offset:36896
	ds_read_b128 v[96:99], v183 offset:53792
	s_waitcnt lgkmcnt(3)
	v_mfma_f32_32x32x16_bf16 v[16:31], v[84:87], v[32:35], v[16:31]
	s_waitcnt lgkmcnt(2)
	v_mfma_f32_32x32x16_bf16 v[0:15], v[88:91], v[32:35], v[0:15]
	v_cvt_pk_bf16_f32 v32, v41, v43
	v_cvt_pk_bf16_f32 v33, v51, v53
	v_cvt_pk_bf16_f32 v34, v57, v62
	v_cvt_pk_bf16_f32 v35, v71, v74
	ds_read_b128 v[84:87], v184 offset:36864
	ds_read_b128 v[88:91], v184 offset:53760
	s_waitcnt lgkmcnt(3)
	v_mfma_f32_32x32x16_bf16 v[16:31], v[92:95], v[32:35], v[16:31]
	s_waitcnt lgkmcnt(2)
	v_mfma_f32_32x32x16_bf16 v[0:15], v[96:99], v[32:35], v[0:15]
	v_cvt_pk_bf16_f32 v32, v52, v54
	v_cvt_pk_bf16_f32 v33, v64, v69
	v_cvt_pk_bf16_f32 v34, v72, v77
	v_cvt_pk_bf16_f32 v35, v109, v112
	ds_read_b128 v[92:95], v184 offset:36896
	ds_read_b128 v[96:99], v184 offset:53792
	s_waitcnt lgkmcnt(3)
	v_mfma_f32_32x32x16_bf16 v[16:31], v[84:87], v[32:35], v[16:31]
	s_waitcnt lgkmcnt(2)
	v_mfma_f32_32x32x16_bf16 v[0:15], v[88:91], v[32:35], v[0:15]
	v_cvt_pk_bf16_f32 v32, v67, v70
	v_cvt_pk_bf16_f32 v33, v79, v107
	v_cvt_pk_bf16_f32 v34, v111, v114
	v_cvt_pk_bf16_f32 v35, v123, v126
	ds_read_b128 v[84:87], v185 offset:36864
	ds_read_b128 v[88:91], v185 offset:53760
	s_waitcnt lgkmcnt(3)
	v_mfma_f32_32x32x16_bf16 v[16:31], v[92:95], v[32:35], v[16:31]
	s_waitcnt lgkmcnt(2)
	v_mfma_f32_32x32x16_bf16 v[0:15], v[96:99], v[32:35], v[0:15]
	v_cvt_pk_bf16_f32 v32, v104, v110
	v_cvt_pk_bf16_f32 v33, v117, v121
	v_cvt_pk_bf16_f32 v34, v125, v127
	v_cvt_pk_bf16_f32 v35, v128, v129
	ds_read_b128 v[92:95], v185 offset:36896
	ds_read_b128 v[96:99], v185 offset:53792
	s_waitcnt lgkmcnt(3)
	v_mfma_f32_32x32x16_bf16 v[16:31], v[84:87], v[32:35], v[16:31]
	s_waitcnt lgkmcnt(2)
	v_mfma_f32_32x32x16_bf16 v[0:15], v[88:91], v[32:35], v[0:15]
	v_cvt_pk_bf16_f32 v32, v113, v115
	v_cvt_pk_bf16_f32 v33, v116, v118
	v_cvt_pk_bf16_f32 v34, v119, v120
	v_cvt_pk_bf16_f32 v35, v122, v124
	ds_read_b128 v[84:87], v187 offset:36864
	ds_read_b128 v[88:91], v187 offset:53760
	s_waitcnt lgkmcnt(3)
	v_mfma_f32_32x32x16_bf16 v[16:31], v[92:95], v[32:35], v[16:31]
	s_waitcnt lgkmcnt(2)
	v_mfma_f32_32x32x16_bf16 v[0:15], v[96:99], v[32:35], v[0:15]
	v_cvt_pk_bf16_f32 v32, v73, v75
	v_cvt_pk_bf16_f32 v33, v76, v78
	v_cvt_pk_bf16_f32 v34, v80, v105
	v_cvt_pk_bf16_f32 v35, v106, v108
	ds_read_b128 v[92:95], v187 offset:36896
	ds_read_b128 v[96:99], v187 offset:53792
	s_waitcnt lgkmcnt(3)
	v_mfma_f32_32x32x16_bf16 v[16:31], v[84:87], v[32:35], v[16:31]
	s_waitcnt lgkmcnt(2)
	v_mfma_f32_32x32x16_bf16 v[0:15], v[88:91], v[32:35], v[0:15]
	v_cvt_pk_bf16_f32 v32, v56, v58
	v_cvt_pk_bf16_f32 v33, v59, v61
	v_cvt_pk_bf16_f32 v34, v63, v65
	v_cvt_pk_bf16_f32 v35, v66, v68
	s_waitcnt lgkmcnt(1)
	v_mfma_f32_32x32x16_bf16 v[16:31], v[92:95], v[32:35], v[16:31]
	s_waitcnt lgkmcnt(0)
	v_mfma_f32_32x32x16_bf16 v[0:15], v[96:99], v[32:35], v[0:15]
	v_add_f32_e32 v32, v46, v47
	v_add_f32_e32 v32, v48, v32
	v_div_scale_f32 v33, s[0:1], v32, v32, 1.0
	v_rcp_f32_e32 v34, v33
	s_mov_b64 s[0:1], 0
	v_fma_f32 v35, -v33, v34, 1.0
	v_fmac_f32_e32 v34, v35, v34
	v_div_scale_f32 v35, vcc, 1.0, v32, 1.0
	v_mul_f32_e32 v36, v35, v34
	v_fma_f32 v37, -v33, v36, v35
	v_fmac_f32_e32 v36, v37, v34
	v_fma_f32 v33, -v33, v36, v35
	v_div_fmas_f32 v33, v33, v34, v36
	v_div_fixup_f32 v34, v33, v32, 1.0
	v_lshrrev_b64 v[32:33], 2, v[160:161]
	v_and_b32_e32 v33, 0x3ffff, v33
	v_and_b32_e32 v32, 0xffffffe0, v32
	v_lshlrev_b32_e32 v35, 6, v160
	v_lshlrev_b32_e32 v37, 2, v160
	v_lshl_add_u64 v[32:33], v[32:33], 0, s[34:35]
	v_and_b32_e32 v35, 0x3c0, v35
	v_lshlrev_b32_e32 v36, 7, v160
	v_and_b32_e32 v37, 32, v37
	v_and_b32_e32 v36, 0x3800, v36
	v_lshlrev_b64 v[32:33], 14, v[32:33]
	v_mul_f32_e32 v16, v34, v16
	v_mul_f32_e32 v17, v34, v17
	v_or3_b32 v39, v137, v35, v37
	v_lshl_add_u64 v[32:33], s[80:81], 0, v[32:33]
	v_cvt_pk_bf16_f32 v16, v16, v17
	v_mul_f32_e32 v17, v34, v18
	v_mul_f32_e32 v18, v34, v19
	v_or_b32_e32 v80, v39, v36
	v_or_b32_e32 v38, 0x400, v36
	v_cvt_pk_bf16_f32 v17, v17, v18
	v_lshl_add_u64 v[18:19], v[32:33], 0, v[80:81]
	v_mul_f32_e32 v0, v34, v0
	v_mul_f32_e32 v1, v34, v1
	global_store_dwordx2 v[18:19], v[16:17], off
	v_cvt_pk_bf16_f32 v0, v0, v1
	v_mul_f32_e32 v1, v34, v2
	v_mul_f32_e32 v2, v34, v3
	v_or_b32_e32 v80, v39, v38
	v_cvt_pk_bf16_f32 v1, v1, v2
	v_lshl_add_u64 v[2:3], v[32:33], 0, v[80:81]
	global_store_dwordx2 v[2:3], v[0:1], off
	v_mul_f32_e32 v0, v34, v20
	v_mul_f32_e32 v1, v34, v21
	v_or3_b32 v16, v165, v35, v37
	v_cvt_pk_bf16_f32 v0, v0, v1
	v_mul_f32_e32 v1, v34, v22
	v_mul_f32_e32 v2, v34, v23
	v_or_b32_e32 v80, v16, v36
	v_cvt_pk_bf16_f32 v1, v1, v2
	v_lshl_add_u64 v[2:3], v[32:33], 0, v[80:81]
	global_store_dwordx2 v[2:3], v[0:1], off
	v_mul_f32_e32 v0, v34, v4
	v_mul_f32_e32 v1, v34, v5
	v_cvt_pk_bf16_f32 v0, v0, v1
	v_mul_f32_e32 v1, v34, v6
	v_mul_f32_e32 v2, v34, v7
	v_or_b32_e32 v80, v16, v38
	v_cvt_pk_bf16_f32 v1, v1, v2
	v_lshl_add_u64 v[2:3], v[32:33], 0, v[80:81]
	global_store_dwordx2 v[2:3], v[0:1], off
	v_mul_f32_e32 v0, v34, v24
	v_mul_f32_e32 v1, v34, v25
	v_bitop3_b32 v4, v166, v37, v35 bitop3:0x36
	v_cvt_pk_bf16_f32 v0, v0, v1
	v_mul_f32_e32 v1, v34, v26
	v_mul_f32_e32 v2, v34, v27
	v_or_b32_e32 v80, v4, v36
	v_cvt_pk_bf16_f32 v1, v1, v2
	v_lshl_add_u64 v[2:3], v[32:33], 0, v[80:81]
	global_store_dwordx2 v[2:3], v[0:1], off
	v_mul_f32_e32 v0, v34, v8
	v_mul_f32_e32 v1, v34, v9
	v_cvt_pk_bf16_f32 v0, v0, v1
	v_mul_f32_e32 v1, v34, v10
	v_mul_f32_e32 v2, v34, v11
	v_or_b32_e32 v80, v4, v38
	v_cvt_pk_bf16_f32 v1, v1, v2
	v_lshl_add_u64 v[2:3], v[32:33], 0, v[80:81]
	global_store_dwordx2 v[2:3], v[0:1], off
	v_mul_f32_e32 v0, v34, v28
	v_mul_f32_e32 v1, v34, v29
	v_bitop3_b32 v4, v167, v37, v35 bitop3:0x36
	v_cvt_pk_bf16_f32 v0, v0, v1
	v_mul_f32_e32 v1, v34, v30
	v_mul_f32_e32 v2, v34, v31
	v_or_b32_e32 v80, v4, v36
	v_cvt_pk_bf16_f32 v1, v1, v2
	v_lshl_add_u64 v[2:3], v[32:33], 0, v[80:81]
	global_store_dwordx2 v[2:3], v[0:1], off
	v_mul_f32_e32 v0, v34, v12
	v_mul_f32_e32 v1, v34, v13
	v_cvt_pk_bf16_f32 v0, v0, v1
	v_mul_f32_e32 v1, v34, v14
	v_mul_f32_e32 v2, v34, v15
	v_or_b32_e32 v80, v4, v38
	v_cvt_pk_bf16_f32 v1, v1, v2
	v_lshl_add_u64 v[2:3], v[32:33], 0, v[80:81]
	global_store_dwordx2 v[2:3], v[0:1], off

.LBB0_486:
	s_waitcnt lgkmcnt(0)
	s_barrier
	ds_read_b128 v[122:125], v119
	ds_read_b128 v[126:129], v120
	ds_read_b128 v[130:133], v121
	ds_read_b128 v[168:171], v119 offset:32
	ds_read_b128 v[172:175], v120 offset:32
	ds_read_b128 v[176:179], v121 offset:32
	ds_read_b128 v[180:183], v119 offset:64
	ds_read_b128 v[184:187], v120 offset:64
	ds_read_b128 v[188:191], v121 offset:64
	v_add_lshl_u32 v80, v50, s16, 2
	s_or_b32 s6, s16, s31
	v_lshl_add_u64 v[78:79], s[14:15], 0, v[50:51]
	s_lshr_b32 s6, s6, 6
	s_or_b32 s6, s6, 16
	v_readlane_b32 s38, v253, 57
	v_readlane_b32 s39, v253, 58
	s_mov_b32 s17, s35
	s_waitcnt lgkmcnt(6)
	v_mfma_f32_32x32x16_bf16 v[16:31], v[122:125], v[126:129], 0
	v_mfma_f32_32x32x16_bf16 v[0:15], v[122:125], v[130:133], 0
	ds_read_b128 v[122:125], v119 offset:96
	ds_read_b128 v[126:129], v120 offset:96
	ds_read_b128 v[130:133], v121 offset:96
	s_waitcnt lgkmcnt(6)
	v_mfma_f32_32x32x16_bf16 v[16:31], v[168:171], v[172:175], v[16:31]
	v_mfma_f32_32x32x16_bf16 v[0:15], v[168:171], v[176:179], v[0:15]
	ds_read_b128 v[168:171], v119 offset:128
	ds_read_b128 v[176:179], v121 offset:128
	s_waitcnt lgkmcnt(5)
	v_mfma_f32_32x32x16_bf16 v[16:31], v[180:183], v[184:187], v[16:31]
	v_mfma_f32_32x32x16_bf16 v[0:15], v[180:183], v[188:191], v[0:15]
	ds_read_b128 v[180:183], v119 offset:160
	ds_read_b128 v[188:191], v121 offset:160
	s_waitcnt lgkmcnt(4)
	v_mfma_f32_32x32x16_bf16 v[16:31], v[122:125], v[126:129], v[16:31]
	v_mfma_f32_32x32x16_bf16 v[0:15], v[122:125], v[130:133], v[0:15]
	ds_read_b128 v[122:125], v119 offset:192
	ds_read_b128 v[130:133], v121 offset:192
	s_waitcnt lgkmcnt(4)
	v_mfma_f32_32x32x16_bf16 v[0:15], v[168:171], v[176:179], v[0:15]
	ds_read_b128 v[168:171], v119 offset:224
	ds_read_b128 v[176:179], v121 offset:224
	s_waitcnt lgkmcnt(4)
	v_mfma_f32_32x32x16_bf16 v[0:15], v[180:183], v[188:191], v[0:15]
	s_waitcnt lgkmcnt(2)
	v_mfma_f32_32x32x16_bf16 v[0:15], v[122:125], v[130:133], v[0:15]
	s_waitcnt lgkmcnt(0)
	v_mfma_f32_32x32x16_bf16 v[0:15], v[168:171], v[176:179], v[0:15]
	v_lshrrev_b64 v[122:123], 2, v[78:79]
	v_lshlrev_b32_e32 v80, 6, v78
	v_and_b32_e32 v79, 0xffffffe0, v122
	v_and_or_b32 v125, v80, s43, v137
	s_waitcnt vmcnt(7)
	v_lshlrev_b32_e32 v80, 16, v76
	v_and_b32_e32 v76, 0xffff0000, v76
	v_or_b32_e32 v122, s6, v79
	v_lshrrev_b32_e32 v79, 3, v78
	v_and_or_b32 v79, v79, 14, s42
	v_lshlrev_b32_e32 v78, 2, v78
	v_lshlrev_b32_e32 v126, 10, v79
	v_and_b32_e32 v127, 32, v78
	v_lshlrev_b64 v[78:79], 14, v[122:123]
	v_lshl_add_u64 v[78:79], s[38:39], 0, v[78:79]
	s_waitcnt vmcnt(0)
	v_add_f32_e32 v16, v150, v16
	v_add_f32_e32 v17, v150, v17
	v_mul_f32_e32 v16, v16, v80
	v_mul_f32_e32 v17, v17, v76
	v_cvt_pk_bf16_f32 v16, v16, v17
	v_lshlrev_b32_e32 v17, 16, v77
	v_add_f32_e32 v18, v150, v18
	v_mul_f32_e32 v17, v18, v17
	v_and_b32_e32 v18, 0xffff0000, v77
	v_add_f32_e32 v19, v150, v19
	v_mul_f32_e32 v18, v19, v18
	v_or3_b32 v80, v125, v127, v126
	v_cvt_pk_bf16_f32 v17, v17, v18
	v_lshl_add_u64 v[18:19], v[78:79], 0, v[80:81]
	global_store_dwordx2 v[18:19], v[16:17], off
	v_lshlrev_b32_e32 v16, 16, v74
	v_add_f32_e32 v17, v150, v20
	v_mul_f32_e32 v16, v17, v16
	v_and_b32_e32 v17, 0xffff0000, v74
	v_add_f32_e32 v18, v150, v21
	v_mul_f32_e32 v17, v18, v17
	v_cvt_pk_bf16_f32 v16, v16, v17
	v_lshlrev_b32_e32 v17, 16, v75
	v_add_f32_e32 v18, v150, v22
	v_mul_f32_e32 v17, v18, v17
	v_and_b32_e32 v18, 0xffff0000, v75
	v_add_f32_e32 v19, v150, v23
	v_mul_f32_e32 v18, v19, v18
	v_or_b32_e32 v80, 16, v80
	v_cvt_pk_bf16_f32 v17, v17, v18
	v_lshl_add_u64 v[18:19], v[78:79], 0, v[80:81]
	global_store_dwordx2 v[18:19], v[16:17], off
	v_lshlrev_b32_e32 v16, 16, v72
	v_add_f32_e32 v17, v150, v24
	v_mul_f32_e32 v16, v17, v16
	v_and_b32_e32 v17, 0xffff0000, v72
	v_add_f32_e32 v18, v150, v25
	v_mul_f32_e32 v17, v18, v17
	v_cvt_pk_bf16_f32 v16, v16, v17
	v_lshlrev_b32_e32 v17, 16, v73
	v_add_f32_e32 v18, v150, v26
	v_mul_f32_e32 v17, v18, v17
	v_and_b32_e32 v18, 0xffff0000, v73
	v_add_f32_e32 v19, v150, v27
	v_mul_f32_e32 v18, v19, v18
	v_cvt_pk_bf16_f32 v17, v17, v18
	v_or_b32_e32 v18, 32, v125
	v_bitop3_b32 v80, v18, v126, v127 bitop3:0xde
	v_lshl_add_u64 v[18:19], v[78:79], 0, v[80:81]
	global_store_dwordx2 v[18:19], v[16:17], off
	v_lshlrev_b32_e32 v16, 16, v70
	v_add_f32_e32 v17, v150, v28
	v_mul_f32_e32 v16, v17, v16
	v_and_b32_e32 v17, 0xffff0000, v70
	v_add_f32_e32 v18, v150, v29
	v_mul_f32_e32 v17, v18, v17
	v_cvt_pk_bf16_f32 v16, v16, v17
	v_lshlrev_b32_e32 v17, 16, v71
	v_add_f32_e32 v18, v150, v30
	v_mul_f32_e32 v17, v18, v17
	v_and_b32_e32 v18, 0xffff0000, v71
	v_add_f32_e32 v19, v150, v31
	v_mul_f32_e32 v18, v19, v18
	v_cvt_pk_bf16_f32 v17, v17, v18
	v_or_b32_e32 v18, 48, v125
	v_bitop3_b32 v80, v18, v126, v127 bitop3:0xde
	v_lshl_add_u64 v[18:19], v[78:79], 0, v[80:81]
	global_store_dwordx2 v[18:19], v[16:17], off
	v_lshl_add_u64 v[16:17], s[14:15], 0, v[48:49]
	v_lshrrev_b64 v[18:19], 2, v[16:17]
	v_and_b32_e32 v17, 0xffffffe0, v18
	v_or_b32_e32 v18, s6, v17
	v_lshrrev_b32_e32 v17, 3, v16
	v_and_b32_e32 v19, 0x3ffff, v19
	v_and_or_b32 v17, v17, 14, s42
	v_lshlrev_b32_e32 v21, 6, v16
	v_lshlrev_b32_e32 v16, 2, v16
	v_lshlrev_b32_e32 v22, 10, v17
	v_and_b32_e32 v23, 32, v16
	v_lshlrev_b64 v[16:17], 14, v[18:19]
	v_lshlrev_b32_e32 v18, 16, v68
	v_and_or_b32 v21, v21, s43, v137
	v_lshl_add_u64 v[16:17], s[38:39], 0, v[16:17]
	v_or3_b32 v80, v21, v23, v22
	v_readlane_b32 s6, v254, 23
	v_readlane_b32 s7, v254, 24
	s_and_b64 vcc, exec, s[6:7]
	s_mov_b32 s6, s18
	s_nop 0
	v_add_f32_e32 v0, v151, v0
	v_mul_f32_e32 v0, v0, v18
	v_and_b32_e32 v18, 0xffff0000, v68
	v_add_f32_e32 v1, v151, v1
	v_mul_f32_e32 v1, v1, v18
	v_cvt_pk_bf16_f32 v0, v0, v1
	v_lshlrev_b32_e32 v1, 16, v69
	v_add_f32_e32 v2, v151, v2
	v_mul_f32_e32 v1, v2, v1
	v_and_b32_e32 v2, 0xffff0000, v69
	v_add_f32_e32 v3, v151, v3
	v_mul_f32_e32 v2, v3, v2
	v_cvt_pk_bf16_f32 v1, v1, v2
	v_lshl_add_u64 v[2:3], v[16:17], 0, v[80:81]
	global_store_dwordx2 v[2:3], v[0:1], off
	v_lshlrev_b32_e32 v0, 16, v66
	v_add_f32_e32 v1, v151, v4
	v_mul_f32_e32 v0, v1, v0
	v_and_b32_e32 v1, 0xffff0000, v66
	v_add_f32_e32 v2, v151, v5
	v_mul_f32_e32 v1, v2, v1
	v_cvt_pk_bf16_f32 v0, v0, v1
	v_lshlrev_b32_e32 v1, 16, v67
	v_add_f32_e32 v2, v151, v6
	v_mul_f32_e32 v1, v2, v1
	v_and_b32_e32 v2, 0xffff0000, v67
	v_add_f32_e32 v3, v151, v7
	v_mul_f32_e32 v2, v3, v2
	v_or_b32_e32 v80, 16, v80
	v_cvt_pk_bf16_f32 v1, v1, v2
	v_lshl_add_u64 v[2:3], v[16:17], 0, v[80:81]
	global_store_dwordx2 v[2:3], v[0:1], off
	v_lshlrev_b32_e32 v0, 16, v64
	v_add_f32_e32 v1, v151, v8
	v_mul_f32_e32 v0, v1, v0
	v_and_b32_e32 v1, 0xffff0000, v64
	v_add_f32_e32 v2, v151, v9
	v_mul_f32_e32 v1, v2, v1
	v_cvt_pk_bf16_f32 v0, v0, v1
	v_lshlrev_b32_e32 v1, 16, v65
	v_add_f32_e32 v2, v151, v10
	v_mul_f32_e32 v1, v2, v1
	v_and_b32_e32 v2, 0xffff0000, v65
	v_add_f32_e32 v3, v151, v11
	v_mul_f32_e32 v2, v3, v2
	v_cvt_pk_bf16_f32 v1, v1, v2
	v_or_b32_e32 v2, 32, v21
	v_bitop3_b32 v80, v2, v22, v23 bitop3:0xde
	v_lshl_add_u64 v[2:3], v[16:17], 0, v[80:81]
	global_store_dwordx2 v[2:3], v[0:1], off
	v_lshlrev_b32_e32 v0, 16, v62
	v_add_f32_e32 v1, v151, v12
	v_mul_f32_e32 v0, v1, v0
	v_and_b32_e32 v1, 0xffff0000, v62
	v_add_f32_e32 v2, v151, v13
	v_mul_f32_e32 v1, v2, v1
	v_cvt_pk_bf16_f32 v0, v0, v1
	v_lshlrev_b32_e32 v1, 16, v63
	v_add_f32_e32 v2, v151, v14
	v_mul_f32_e32 v1, v2, v1
	v_and_b32_e32 v2, 0xffff0000, v63
	v_add_f32_e32 v3, v151, v15
	v_mul_f32_e32 v2, v3, v2
	v_cvt_pk_bf16_f32 v1, v1, v2
	v_or_b32_e32 v2, 48, v21
	v_bitop3_b32 v80, v2, v22, v23 bitop3:0xde
	v_lshl_add_u64 v[2:3], v[16:17], 0, v[80:81]
	global_store_dwordx2 v[2:3], v[0:1], off
	s_cbranch_vccnz .LBB0_488
	v_readlane_b32 s6, v250, 4
	s_add_i32 s6, s28, s6

.LBB0_595:
	s_cmp_lg_u32 s39, 0x40000
	s_cbranch_scc1 .LBB0_594
	s_mov_b64 s[94:95], s[4:5]
	s_nop 0
	v_lshl_add_u64 v[82:83], s[94:95], 0, v[220:221]
	global_load_dwordx4 v[152:155], v[82:83], off
	s_mov_b64 s[94:95], s[6:7]
	s_nop 0
	v_lshl_add_u64 v[82:83], s[94:95], 0, v[220:221]
	global_load_dwordx4 v[156:159], v[82:83], off
	s_mov_b64 s[94:95], s[8:9]
	s_nop 0
	v_lshl_add_u64 v[82:83], s[94:95], 0, v[220:221]
	global_load_dwordx4 v[160:163], v[82:83], off
	s_mov_b64 s[94:95], s[10:11]
	s_nop 0
	v_lshl_add_u64 v[82:83], s[94:95], 0, v[220:221]
	global_load_dwordx4 v[164:167], v[82:83], off
	s_mov_b64 s[94:95], s[12:13]
	s_nop 0
	v_lshl_add_u64 v[82:83], s[94:95], 0, v[220:221]
	global_load_dwordx4 v[168:171], v[82:83], off
	s_mov_b64 s[94:95], s[14:15]
	s_nop 0
	v_lshl_add_u64 v[82:83], s[94:95], 0, v[220:221]
	global_load_dwordx4 v[172:175], v[82:83], off
	s_mov_b64 s[94:95], s[16:17]
	s_nop 0
	v_lshl_add_u64 v[82:83], s[94:95], 0, v[220:221]
	global_load_dwordx4 v[176:179], v[82:83], off
	s_mov_b64 s[94:95], s[18:19]
	s_nop 0
	v_lshl_add_u64 v[82:83], s[94:95], 0, v[220:221]
	global_load_dwordx4 v[180:183], v[82:83], off
	v_lshl_add_u64 v[82:83], s[28:29], 0, v[220:221]
	global_load_dwordx4 v[184:187], v[82:83], off
	v_lshl_add_u64 v[82:83], s[40:41], 0, v[220:221]
	global_load_dwordx4 v[188:191], v[82:83], off
	v_lshl_add_u64 v[82:83], s[42:43], 0, v[220:221]
	global_load_dwordx4 v[192:195], v[82:83], off
	v_lshl_add_u64 v[82:83], s[44:45], 0, v[220:221]
	global_load_dwordx4 v[196:199], v[82:83], off
	v_lshl_add_u64 v[82:83], s[52:53], 0, v[220:221]
	global_load_dwordx4 v[200:203], v[82:83], off
	v_lshl_add_u64 v[82:83], s[56:57], 0, v[220:221]
	global_load_dwordx4 v[204:207], v[82:83], off
	v_lshl_add_u64 v[82:83], s[68:69], 0, v[220:221]
	global_load_dwordx4 v[228:231], v[82:83], off
	v_lshl_add_u64 v[82:83], s[70:71], 0, v[220:221]
	global_load_dwordx4 v[240:243], v[82:83], off
	s_mov_b64 s[94:95], s[28:29]
	s_waitcnt vmcnt(15)
	v_lshlrev_b32_e32 v82, 16, v152
	v_and_b32_e32 v83, 0xffff0000, v152
	v_lshlrev_b32_e32 v152, 16, v153
	v_and_b32_e32 v153, 0xffff0000, v153
	v_pk_mul_f32 v[148:149], v[148:149], v[82:83]
	v_lshlrev_b32_e32 v82, 16, v154
	v_and_b32_e32 v83, 0xffff0000, v154
	v_pk_mul_f32 v[150:151], v[150:151], v[152:153]
	v_lshlrev_b32_e32 v152, 16, v155
	v_and_b32_e32 v153, 0xffff0000, v155
	v_pk_mul_f32 v[144:145], v[144:145], v[82:83]
	s_waitcnt vmcnt(14)
	v_lshlrev_b32_e32 v82, 16, v156
	v_and_b32_e32 v83, 0xffff0000, v156
	v_pk_mul_f32 v[146:147], v[146:147], v[152:153]
	v_lshlrev_b32_e32 v152, 16, v157
	v_and_b32_e32 v153, 0xffff0000, v157
	v_pk_mul_f32 v[140:141], v[140:141], v[82:83]
	v_lshlrev_b32_e32 v82, 16, v158
	v_and_b32_e32 v83, 0xffff0000, v158
	v_pk_mul_f32 v[142:143], v[142:143], v[152:153]
	v_lshlrev_b32_e32 v152, 16, v159
	v_and_b32_e32 v153, 0xffff0000, v159
	v_pk_mul_f32 v[136:137], v[136:137], v[82:83]
	s_waitcnt vmcnt(13)
	v_lshlrev_b32_e32 v82, 16, v160
	v_and_b32_e32 v83, 0xffff0000, v160
	v_pk_mul_f32 v[138:139], v[138:139], v[152:153]
	v_lshlrev_b32_e32 v152, 16, v161
	v_and_b32_e32 v153, 0xffff0000, v161
	v_pk_mul_f32 v[132:133], v[132:133], v[82:83]
	v_lshlrev_b32_e32 v82, 16, v162
	v_and_b32_e32 v83, 0xffff0000, v162
	v_pk_mul_f32 v[134:135], v[134:135], v[152:153]
	v_lshlrev_b32_e32 v152, 16, v163
	v_and_b32_e32 v153, 0xffff0000, v163
	v_pk_mul_f32 v[128:129], v[128:129], v[82:83]
	s_waitcnt vmcnt(12)
	v_lshlrev_b32_e32 v82, 16, v164
	v_and_b32_e32 v83, 0xffff0000, v164
	v_pk_mul_f32 v[130:131], v[130:131], v[152:153]
	v_lshlrev_b32_e32 v152, 16, v165
	v_and_b32_e32 v153, 0xffff0000, v165
	v_pk_mul_f32 v[124:125], v[124:125], v[82:83]
	v_lshlrev_b32_e32 v82, 16, v166
	v_and_b32_e32 v83, 0xffff0000, v166
	v_pk_mul_f32 v[126:127], v[126:127], v[152:153]
	v_lshlrev_b32_e32 v152, 16, v167
	v_and_b32_e32 v153, 0xffff0000, v167
	v_pk_mul_f32 v[120:121], v[120:121], v[82:83]
	s_waitcnt vmcnt(11)
	v_lshlrev_b32_e32 v82, 16, v168
	v_and_b32_e32 v83, 0xffff0000, v168
	v_pk_mul_f32 v[122:123], v[122:123], v[152:153]
	v_lshlrev_b32_e32 v152, 16, v169
	v_and_b32_e32 v153, 0xffff0000, v169
	v_pk_mul_f32 v[116:117], v[116:117], v[82:83]
	v_lshlrev_b32_e32 v82, 16, v170
	v_and_b32_e32 v83, 0xffff0000, v170
	v_pk_mul_f32 v[118:119], v[118:119], v[152:153]
	v_lshlrev_b32_e32 v152, 16, v171
	v_and_b32_e32 v153, 0xffff0000, v171
	v_pk_mul_f32 v[112:113], v[112:113], v[82:83]
	s_waitcnt vmcnt(10)
	v_lshlrev_b32_e32 v82, 16, v172
	v_and_b32_e32 v83, 0xffff0000, v172
	v_pk_mul_f32 v[114:115], v[114:115], v[152:153]
	v_lshlrev_b32_e32 v152, 16, v173
	v_and_b32_e32 v153, 0xffff0000, v173
	v_pk_mul_f32 v[108:109], v[108:109], v[82:83]
	v_lshlrev_b32_e32 v82, 16, v174
	v_and_b32_e32 v83, 0xffff0000, v174
	v_pk_mul_f32 v[110:111], v[110:111], v[152:153]
	v_lshlrev_b32_e32 v152, 16, v175
	v_and_b32_e32 v153, 0xffff0000, v175
	v_pk_mul_f32 v[104:105], v[104:105], v[82:83]
	s_waitcnt vmcnt(9)
	v_lshlrev_b32_e32 v82, 16, v176
	v_and_b32_e32 v83, 0xffff0000, v176
	v_pk_mul_f32 v[106:107], v[106:107], v[152:153]
	v_lshlrev_b32_e32 v152, 16, v177
	v_and_b32_e32 v153, 0xffff0000, v177
	v_pk_mul_f32 v[76:77], v[76:77], v[82:83]
	v_lshlrev_b32_e32 v82, 16, v178
	v_and_b32_e32 v83, 0xffff0000, v178
	v_pk_mul_f32 v[78:79], v[78:79], v[152:153]
	v_lshlrev_b32_e32 v152, 16, v179
	v_and_b32_e32 v153, 0xffff0000, v179
	v_pk_mul_f32 v[72:73], v[72:73], v[82:83]
	s_waitcnt vmcnt(8)
	v_lshlrev_b32_e32 v82, 16, v180
	v_and_b32_e32 v83, 0xffff0000, v180
	v_pk_mul_f32 v[74:75], v[74:75], v[152:153]
	v_lshlrev_b32_e32 v152, 16, v181
	v_and_b32_e32 v153, 0xffff0000, v181
	v_pk_mul_f32 v[68:69], v[68:69], v[82:83]
	v_lshlrev_b32_e32 v82, 16, v182
	v_and_b32_e32 v83, 0xffff0000, v182
	v_pk_mul_f32 v[70:71], v[70:71], v[152:153]
	v_lshlrev_b32_e32 v152, 16, v183
	v_and_b32_e32 v153, 0xffff0000, v183
	v_pk_mul_f32 v[64:65], v[64:65], v[82:83]
	v_pk_mul_f32 v[66:67], v[66:67], v[152:153]
	s_waitcnt vmcnt(7)
	v_lshlrev_b32_e32 v82, 16, v184
	v_and_b32_e32 v83, 0xffff0000, v184
	v_lshlrev_b32_e32 v152, 16, v185
	v_and_b32_e32 v153, 0xffff0000, v185
	v_pk_mul_f32 v[62:63], v[62:63], v[152:153]
	v_pk_mul_f32 v[60:61], v[60:61], v[82:83]
	v_lshlrev_b32_e32 v82, 16, v186
	v_and_b32_e32 v83, 0xffff0000, v186
	v_lshlrev_b32_e32 v152, 16, v187
	v_and_b32_e32 v153, 0xffff0000, v187
	v_pk_mul_f32 v[58:59], v[58:59], v[152:153]
	v_pk_mul_f32 v[56:57], v[56:57], v[82:83]
	s_waitcnt vmcnt(6)
	v_lshlrev_b32_e32 v82, 16, v188
	v_and_b32_e32 v83, 0xffff0000, v188
	v_lshlrev_b32_e32 v152, 16, v189
	v_and_b32_e32 v153, 0xffff0000, v189
	v_pk_mul_f32 v[54:55], v[54:55], v[152:153]
	v_pk_mul_f32 v[52:53], v[52:53], v[82:83]
	v_lshlrev_b32_e32 v82, 16, v190
	v_and_b32_e32 v83, 0xffff0000, v190
	v_lshlrev_b32_e32 v152, 16, v191
	v_and_b32_e32 v153, 0xffff0000, v191
	v_pk_mul_f32 v[50:51], v[50:51], v[152:153]
	v_pk_mul_f32 v[48:49], v[48:49], v[82:83]
	s_waitcnt vmcnt(5)
	v_lshlrev_b32_e32 v82, 16, v192
	v_and_b32_e32 v83, 0xffff0000, v192
	v_lshlrev_b32_e32 v152, 16, v193
	v_and_b32_e32 v153, 0xffff0000, v193
	v_pk_mul_f32 v[46:47], v[46:47], v[152:153]
	v_pk_mul_f32 v[44:45], v[44:45], v[82:83]
	v_lshlrev_b32_e32 v82, 16, v194
	v_and_b32_e32 v83, 0xffff0000, v194
	v_lshlrev_b32_e32 v152, 16, v195
	v_and_b32_e32 v153, 0xffff0000, v195
	v_pk_mul_f32 v[42:43], v[42:43], v[152:153]
	v_pk_mul_f32 v[40:41], v[40:41], v[82:83]
	s_waitcnt vmcnt(4)
	v_lshlrev_b32_e32 v82, 16, v196
	v_and_b32_e32 v83, 0xffff0000, v196
	v_lshlrev_b32_e32 v152, 16, v197
	v_and_b32_e32 v153, 0xffff0000, v197
	v_pk_mul_f32 v[38:39], v[38:39], v[152:153]
	v_pk_mul_f32 v[36:37], v[36:37], v[82:83]
	v_lshlrev_b32_e32 v82, 16, v198
	v_and_b32_e32 v83, 0xffff0000, v198
	v_lshlrev_b32_e32 v152, 16, v199
	v_and_b32_e32 v153, 0xffff0000, v199
	v_pk_mul_f32 v[34:35], v[34:35], v[152:153]
	v_pk_mul_f32 v[32:33], v[32:33], v[82:83]
	s_waitcnt vmcnt(3)
	v_lshlrev_b32_e32 v82, 16, v200
	v_and_b32_e32 v83, 0xffff0000, v200
	v_lshlrev_b32_e32 v152, 16, v201
	v_and_b32_e32 v153, 0xffff0000, v201
	v_pk_mul_f32 v[30:31], v[30:31], v[152:153]
	v_pk_mul_f32 v[28:29], v[28:29], v[82:83]
	v_lshlrev_b32_e32 v82, 16, v202
	v_and_b32_e32 v83, 0xffff0000, v202
	v_lshlrev_b32_e32 v152, 16, v203
	v_and_b32_e32 v153, 0xffff0000, v203
	v_pk_mul_f32 v[26:27], v[26:27], v[152:153]
	v_pk_mul_f32 v[24:25], v[24:25], v[82:83]
	s_waitcnt vmcnt(2)
	v_lshlrev_b32_e32 v82, 16, v204
	v_and_b32_e32 v83, 0xffff0000, v204
	v_lshlrev_b32_e32 v152, 16, v205
	v_and_b32_e32 v153, 0xffff0000, v205
	v_pk_mul_f32 v[22:23], v[22:23], v[152:153]
	v_pk_mul_f32 v[20:21], v[20:21], v[82:83]
	v_lshlrev_b32_e32 v82, 16, v206
	v_and_b32_e32 v83, 0xffff0000, v206
	v_lshlrev_b32_e32 v152, 16, v207
	v_and_b32_e32 v153, 0xffff0000, v207
	v_pk_mul_f32 v[18:19], v[18:19], v[152:153]
	v_pk_mul_f32 v[16:17], v[16:17], v[82:83]
	s_waitcnt vmcnt(1)
	v_lshlrev_b32_e32 v82, 16, v228
	v_and_b32_e32 v83, 0xffff0000, v228
	v_lshlrev_b32_e32 v152, 16, v229
	v_and_b32_e32 v153, 0xffff0000, v229
	v_pk_mul_f32 v[14:15], v[14:15], v[152:153]
	v_pk_mul_f32 v[12:13], v[12:13], v[82:83]
	v_lshlrev_b32_e32 v82, 16, v230
	v_and_b32_e32 v83, 0xffff0000, v230
	v_lshlrev_b32_e32 v152, 16, v231
	v_and_b32_e32 v153, 0xffff0000, v231
	v_pk_mul_f32 v[10:11], v[10:11], v[152:153]
	v_pk_mul_f32 v[8:9], v[8:9], v[82:83]
	s_waitcnt vmcnt(0)
	v_lshlrev_b32_e32 v82, 16, v240
	v_and_b32_e32 v83, 0xffff0000, v240
	v_lshlrev_b32_e32 v152, 16, v241
	v_and_b32_e32 v153, 0xffff0000, v241
	v_pk_mul_f32 v[6:7], v[6:7], v[152:153]
	v_pk_mul_f32 v[4:5], v[4:5], v[82:83]
	v_lshlrev_b32_e32 v82, 16, v242
	v_and_b32_e32 v83, 0xffff0000, v242
	v_lshlrev_b32_e32 v152, 16, v243
	v_and_b32_e32 v153, 0xffff0000, v243
	v_pk_mul_f32 v[2:3], v[2:3], v[152:153]
	v_pk_mul_f32 v[0:1], v[0:1], v[82:83]
	s_branch .LBB0_594
